# v31 + O3 q-up/kv-up GEMMs fully unrolled with a 3-stage LDS ring (two k-slices in flight, counted vmcnt)
# speedup vs baseline: 1.0036x; 1.0036x over previous
.LBB0_269:
	s_or_b64 exec, exec, s[2:3]
	s_cmpk_lt_i32 s92, 0xf0
	s_cselect_b64 s[4:5], -1, 0
	v_writelane_b32 v242, s4, 6
	s_mul_i32 s2, s39, s38
	s_mul_i32 s33, s2, s33
	v_writelane_b32 v242, s5, 7
	s_load_dwordx2 s[4:5], s[0:1], 0xf8
	v_exp_f32_e32 v156, 0xbfd49a78
	v_exp_f32_e32 v157, 0xc0549a78
	v_exp_f32_e32 v158, 0xc09f73da
	v_exp_f32_e32 v159, 0xc0d49a78
	s_waitcnt lgkmcnt(0)
	s_add_u32 s2, s4, 0x200
	s_addc_u32 s3, s5, 0
	v_writelane_b32 v242, s2, 8
	v_lshl_add_u64 v[0:1], v[0:1], 2, s[4:5]
	v_exp_f32_e32 v160, 0xc104e08b
	v_writelane_b32 v242, s3, 9
	s_add_u32 s2, s4, 0x1000
	s_addc_u32 s3, s5, 0
	v_writelane_b32 v242, s2, 10
	v_exp_f32_e32 v161, 0xc11f73da
	v_exp_f32_e32 v162, 0xc13a0729
	v_writelane_b32 v242, s3, 11
	s_add_u32 s2, s4, 0x1100
	s_addc_u32 s3, s5, 0
	v_writelane_b32 v242, s2, 12
	s_mov_b32 s73, 0
	s_movk_i32 s31, 0x100
	v_writelane_b32 v242, s3, 13
	s_add_u32 s2, s4, 0x1200
	s_addc_u32 s3, s5, 0
	v_writelane_b32 v242, s2, 14
	s_movk_i32 s34, 0x300
	s_mov_b32 s35, 0x2aaaaaab
	v_writelane_b32 v242, s3, 15
	s_add_u32 s2, s4, 0x1300
	s_addc_u32 s3, s5, 0
	v_writelane_b32 v242, s2, 16
	s_cmp_eq_u32 s60, 15
	s_movk_i32 s39, 0xff
	v_writelane_b32 v242, s3, 17
	s_cselect_b64 s[2:3], -1, 0
	v_writelane_b32 v242, s2, 18
	s_cmp_eq_u32 s60, 14
	v_mov_b32_e32 v129, 0
	v_writelane_b32 v242, s3, 19
	s_cselect_b64 s[2:3], -1, 0
	v_writelane_b32 v242, s2, 20
	s_cmp_eq_u32 s60, 13
	v_mov_b32_e32 v163, 0x358637bd
	v_writelane_b32 v242, s3, 21
	s_cselect_b64 s[2:3], -1, 0
	v_writelane_b32 v242, s2, 22
	s_cmp_eq_u32 s60, 12
	s_mov_b64 s[90:91], 0x6f94080
	v_writelane_b32 v242, s3, 23
	s_cselect_b64 s[2:3], -1, 0
	v_writelane_b32 v242, s2, 24
	s_cmp_eq_u32 s60, 11
	s_mov_b64 s[16:17], 0x6fb4080
	v_writelane_b32 v242, s3, 25
	s_cselect_b64 s[2:3], -1, 0
	v_writelane_b32 v242, s2, 26
	s_cmp_eq_u32 s60, 10
	s_load_dwordx4 s[8:11], s[0:1], 0x50
	v_writelane_b32 v242, s3, 27
	s_cselect_b64 s[2:3], -1, 0
	v_writelane_b32 v242, s2, 28
	s_cmp_eq_u32 s60, 9
	s_mov_b64 s[20:21], 0x6fd4080
	v_writelane_b32 v242, s3, 29
	s_cselect_b64 s[2:3], -1, 0
	v_writelane_b32 v242, s2, 30
	s_cmp_eq_u32 s60, 8
	v_mov_b32_e32 v164, 0x26000
	v_writelane_b32 v242, s3, 31
	s_cselect_b64 s[2:3], -1, 0
	v_writelane_b32 v242, s2, 32
	s_cmp_eq_u32 s60, 7
	v_mov_b32_e32 v165, 0x26004
	v_writelane_b32 v242, s3, 33
	s_cselect_b64 s[2:3], -1, 0
	v_writelane_b32 v242, s2, 34
	s_cmp_eq_u32 s60, 6
	v_mov_b32_e32 v166, 1
	v_writelane_b32 v242, s3, 35
	s_cselect_b64 s[2:3], -1, 0
	v_writelane_b32 v242, s2, 36
	s_cmp_eq_u32 s60, 5
	s_movk_i32 s80, 0x90
	v_writelane_b32 v242, s3, 37
	s_cselect_b64 s[2:3], -1, 0
	v_writelane_b32 v242, s2, 38
	s_cmp_eq_u32 s60, 4
	s_mov_b32 s96, 0x3e16c740
	v_writelane_b32 v242, s3, 39
	s_cselect_b64 s[2:3], -1, 0
	v_writelane_b32 v242, s2, 40
	s_cmp_eq_u32 s60, 3
	s_mov_b32 s97, 0x3e38aa3b
	v_writelane_b32 v242, s3, 41
	s_cselect_b64 s[2:3], -1, 0
	v_writelane_b32 v242, s2, 42
	s_cmp_eq_u32 s60, 2
	v_mov_b32_e32 v167, 0x24000
	v_writelane_b32 v242, s3, 43
	s_cselect_b64 s[2:3], -1, 0
	v_writelane_b32 v242, s2, 44
	s_cmp_eq_u32 s60, 1
	v_mov_b32_e32 v168, 0x24400
	v_writelane_b32 v242, s3, 45
	s_cselect_b64 s[2:3], -1, 0
	v_writelane_b32 v242, s2, 46
	s_cmp_eq_u32 s60, 0
	v_mov_b32_e32 v169, 0x3ff
	v_writelane_b32 v242, s3, 47
	s_cselect_b64 s[2:3], -1, 0
	v_writelane_b32 v242, s2, 48
	v_mov_b32_e32 v170, 0xff
	v_mov_b32_e32 v171, 0x400
	v_writelane_b32 v242, s3, 49
	s_mov_b64 s[2:3], 0x1400
	v_lshl_add_u64 v[140:141], v[0:1], 0, s[2:3]
	s_mov_b64 s[2:3], 0x2400
	v_lshl_add_u64 v[142:143], v[0:1], 0, s[2:3]
	s_add_u32 s2, s4, 0x3400
	s_addc_u32 s3, s5, 0
	v_writelane_b32 v242, s2, 50
	v_mov_b32_e32 v172, 0x100
	v_mov_b32_e32 v173, 0xc000
	v_writelane_b32 v242, s3, 51
	s_add_u32 s2, s4, 0x3500
	s_addc_u32 s3, s5, 0
	s_load_dwordx4 s[4:7], s[0:1], 0xd8
	v_writelane_b32 v242, s2, 52
	s_cmpk_lt_i32 s92, 0xb40
	v_mov_b32_e32 v174, 0x28000
	v_writelane_b32 v242, s3, 53
	s_waitcnt lgkmcnt(0)
	v_writelane_b32 v242, s4, 54
	s_load_dwordx2 s[2:3], s[0:1], 0x28
	v_mov_b32_e32 v175, 0x3c000
	v_writelane_b32 v242, s5, 55
	v_writelane_b32 v242, s6, 56
	v_writelane_b32 v242, s7, 57
	s_load_dwordx4 s[4:7], s[0:1], 0xf0
	s_waitcnt lgkmcnt(0)
	v_writelane_b32 v242, s2, 58
	v_mov_b32_e32 v176, 2
	v_mov_b32_e32 v177, 0x24300
	v_writelane_b32 v242, s3, 59
	s_cselect_b64 s[2:3], -1, 0
	v_writelane_b32 v242, s2, 60
	v_mov_b32_e32 v178, 0xfffffa00
	v_mov_b32_e32 v179, 0xfffff800
	v_writelane_b32 v242, s3, 61
	s_add_u32 s2, s6, 0x37c000
	s_addc_u32 s3, s7, 0
	v_writelane_b32 v242, s2, 62
	v_mov_b32_e32 v180, 0xb000
	s_mov_b64 s[22:23], 0
	v_writelane_b32 v242, s3, 63
	s_add_u32 s2, s4, 0x5000000
	s_addc_u32 s3, s5, 0
	v_writelane_b32 v241, s2, 0
	s_barrier
	s_nop 0
	v_writelane_b32 v241, s3, 1
	s_load_dwordx2 s[2:3], s[0:1], 0xc8
	s_waitcnt lgkmcnt(0)
	v_writelane_b32 v241, s2, 2
	s_nop 1
	v_writelane_b32 v241, s3, 3
	s_add_u32 s2, s6, 0x514000
	s_addc_u32 s3, s7, 0
	v_writelane_b32 v241, s2, 4
	s_nop 1
	v_writelane_b32 v241, s3, 5
	s_add_u32 s2, s6, 0x9f94000
	s_addc_u32 s3, s7, 0
	v_writelane_b32 v241, s2, 6
	s_nop 1
	v_writelane_b32 v241, s3, 7
	s_add_u32 s2, s6, 0x8794000
	s_addc_u32 s3, s7, 0
	v_writelane_b32 v241, s2, 8
	s_cmpk_lt_i32 s92, 0x180
	s_nop 0
	v_writelane_b32 v241, s3, 9
	s_cselect_b64 s[2:3], -1, 0
	v_writelane_b32 v241, s2, 10
	s_cmpk_lt_i32 s92, 0x100
	s_nop 0
	v_writelane_b32 v241, s3, 11
	s_cselect_b64 s[2:3], -1, 0
	v_writelane_b32 v241, s2, 12
	s_nop 1
	v_writelane_b32 v241, s3, 13
	s_mov_b64 s[2:3], 0
	v_writelane_b32 v241, s2, 14
	s_nop 1
	v_writelane_b32 v241, s3, 15
	v_writelane_b32 v241, s8, 16
	s_cmp_lg_u64 s[10:11], 0
	s_cselect_b64 s[2:3], -1, 0
	v_writelane_b32 v241, s9, 17
	v_writelane_b32 v241, s10, 18
	v_writelane_b32 v241, s11, 19
	s_load_dwordx8 s[4:11], s[0:1], 0x78
	v_writelane_b32 v241, s2, 20
	s_cmpk_lt_i32 s92, 0x300
	s_cselect_b64 s[0:1], -1, 0
	v_writelane_b32 v241, s3, 21
	s_waitcnt lgkmcnt(0)
	v_writelane_b32 v241, s4, 22
	s_cmpk_lt_i32 s92, 0x780
	s_nop 0
	v_writelane_b32 v241, s5, 23
	v_writelane_b32 v241, s6, 24
	v_writelane_b32 v241, s7, 25
	v_writelane_b32 v241, s8, 26
	v_writelane_b32 v241, s9, 27
	v_writelane_b32 v241, s10, 28
	v_writelane_b32 v241, s11, 29
	v_writelane_b32 v241, s0, 30
	s_nop 1
	v_writelane_b32 v241, s1, 31
	s_cselect_b64 s[0:1], -1, 0
	v_writelane_b32 v241, s0, 32
	s_nop 1
	v_writelane_b32 v241, s1, 33
	s_add_i32 s0, s92, 0xffffff00
	v_writelane_b32 v241, s0, 34
	v_writelane_b32 v241, s92, 35
	v_writelane_b32 v241, s94, 36
	s_nop 1
	v_writelane_b32 v241, s95, 37
	v_writelane_b32 v241, s33, 38
	s_branch .LBB0_273
.Lexit_near:
	s_endpgm
.LBB0_270:
	s_or_b64 exec, exec, s[2:3]
	s_waitcnt vmcnt(0)
	global_atomic_add v[142:143], v166, off
	s_waitcnt vmcnt(0)

.LBB0_486:
	s_andn2_b64 vcc, exec, s[0:1]
	s_cbranch_vccnz .LBB0_492
	s_add_i32 s0, s8, 0xfe40
	s_and_b32 s1, s0, 0xffff
	s_mul_i32 s1, s1, 0xaaab
	s_lshr_b32 s1, s1, 22
	s_mul_i32 s2, s1, 0x60
	v_mov_b32_e32 v4, v155
	s_sub_i32 s0, s0, s2
	s_lshl_b32 s0, s0, 7
	v_ashrrev_i32_e32 v0, 6, v4
	v_lshrrev_b32_e32 v1, 31, v4
	v_lshrrev_b32_e32 v7, 4, v4
	v_add_u32_e32 v5, v0, v1
	v_xor_b32_e32 v3, v7, v4
	s_and_b32 s2, s0, 0xff80
	s_lshl_b32 s9, s1, 8
	v_and_b32_e32 v1, 0x1fffffe, v5
	v_ashrrev_i32_e32 v2, 3, v4
	v_lshlrev_b32_e32 v3, 4, v3
	v_sub_u32_e32 v6, v0, v1
	v_add_u32_e32 v8, s2, v2
	v_mov_b64_e32 v[0:1], s[74:75]
	v_and_b32_e32 v128, 0x70, v3
	v_add_u32_e32 v9, s9, v2
	v_mov_b64_e32 v[2:3], s[70:71]
	v_mad_i64_i32 v[0:1], s[0:1], v8, s34, v[0:1]
	v_mad_i64_i32 v[2:3], s[0:1], v9, s34, v[2:3]
	v_lshlrev_b32_e32 v56, 4, v4
	v_add_u32_e32 v10, 0x2000, v56
	v_readfirstlane_b32 s0, v56
	v_lshl_add_u64 v[0:1], v[0:1], 0, v[128:129]
	s_mov_b32 m0, s0
	s_mov_b64 s[10:11], 0xc000
	v_readfirstlane_b32 s0, v10
	s_barrier
	global_load_lds_dwordx4 v[0:1], off
	v_lshl_add_u64 v[0:1], v[0:1], 0, s[10:11]
	s_mov_b32 m0, s0
	v_add_u32_e32 v10, 0x6000, v56
	global_load_lds_dwordx4 v[0:1], off
	v_lshl_add_u64 v[0:1], v[2:3], 0, v[128:129]
	v_add_u32_e32 v2, 0x4000, v56
	v_lshlrev_b32_e32 v5, 4, v5
	v_readfirstlane_b32 s0, v2
	s_mov_b32 m0, s0
	v_readfirstlane_b32 s0, v10
	global_load_lds_dwordx4 v[0:1], off
	v_lshl_add_u64 v[2:3], v[0:1], 0, s[10:11]
	s_mov_b32 m0, s0
	s_mov_b64 s[0:1], 0x18000
	v_add_u32_e32 v10, 0x8000, v56
	global_load_lds_dwordx4 v[2:3], off
	v_lshl_add_u64 v[2:3], v[0:1], 0, s[0:1]
	v_readfirstlane_b32 s0, v10
	s_mov_b32 m0, s0
	s_mov_b64 s[0:1], 0x24000
	global_load_lds_dwordx4 v[2:3], off
	v_add_u32_e32 v2, 0xa000, v56
	v_lshl_add_u64 v[0:1], v[0:1], 0, s[0:1]
	v_readfirstlane_b32 s0, v2
	s_mov_b32 m0, s0
	v_mad_i64_i32 v[2:3], s[0:1], v9, s34, 0
	global_load_lds_dwordx4 v[0:1], off
	v_mad_i64_i32 v[0:1], s[0:1], v8, s34, 0
	s_movk_i32 s0, 0xffe0
	v_bfe_u32 v10, v4, 5, 1
	v_lshrrev_b32_e32 v8, 1, v4
	v_and_b32_e32 v54, 0xffffffe0, v5
	v_bfi_b32 v5, s0, v5, v4
	v_bfe_u32 v9, v4, 1, 3
	v_lshlrev_b32_e32 v61, 7, v5
	v_bitop3_b32 v5, v10, v8, 7 bitop3:0x78
	v_and_b32_e32 v52, 31, v4
	v_and_b32_e32 v53, 63, v4
	v_lshlrev_b32_e32 v98, 7, v6
	v_lshlrev_b32_e32 v59, 4, v5
	v_bitop3_b32 v5, v10, v9, 2 bitop3:0x36
	v_bitop3_b32 v4, v7, 7, v4 bitop3:0x48
	v_or_b32_e32 v6, v98, v52
	v_lshlrev_b32_e32 v58, 4, v5
	v_bitop3_b32 v5, v10, v9, 4 bitop3:0x36
	v_lshlrev_b32_e32 v4, 4, v4
	v_lshlrev_b32_e32 v60, 7, v6
	v_lshlrev_b32_e32 v57, 4, v5
	v_bitop3_b32 v5, v10, v9, 6 bitop3:0x36
	v_or_b32_e32 v2, v2, v4
	v_or_b32_e32 v0, v0, v4
	v_mov_b32_e32 v16, 0
	v_lshlrev_b32_e32 v55, 4, v5
	v_add_u32_e32 v62, 0x4000, v60
	v_lshl_add_u64 v[48:49], s[82:83], 0, v[2:3]
	v_lshl_add_u64 v[50:51], s[36:37], 0, v[0:1]
	s_mov_b32 s3, 0
	s_mov_b64 s[0:1], 0
	v_mov_b32_e32 v17, v16
	v_mov_b32_e32 v18, v16
	v_mov_b32_e32 v19, v16
	v_mov_b32_e32 v20, v16
	v_mov_b32_e32 v21, v16
	v_mov_b32_e32 v22, v16
	v_mov_b32_e32 v23, v16
	v_mov_b32_e32 v24, v16
	v_mov_b32_e32 v25, v16
	v_mov_b32_e32 v26, v16
	v_mov_b32_e32 v27, v16
	v_mov_b32_e32 v28, v16
	v_mov_b32_e32 v29, v16
	v_mov_b32_e32 v30, v16
	v_mov_b32_e32 v31, v16
	v_mov_b32_e32 v32, v16
	v_mov_b32_e32 v33, v16
	v_mov_b32_e32 v34, v16
	v_mov_b32_e32 v35, v16
	v_mov_b32_e32 v36, v16
	v_mov_b32_e32 v37, v16
	v_mov_b32_e32 v38, v16
	v_mov_b32_e32 v39, v16
	v_mov_b32_e32 v40, v16
	v_mov_b32_e32 v41, v16
	v_mov_b32_e32 v42, v16
	v_mov_b32_e32 v43, v16
	v_mov_b32_e32 v44, v16
	v_mov_b32_e32 v45, v16
	v_mov_b32_e32 v46, v16
	v_mov_b32_e32 v47, v16
	v_mov_b32_e32 v0, v16
	v_mov_b32_e32 v1, v16
	v_mov_b32_e32 v2, v16
	v_mov_b32_e32 v3, v16
	v_mov_b32_e32 v4, v16
	v_mov_b32_e32 v5, v16
	v_mov_b32_e32 v6, v16
	v_mov_b32_e32 v7, v16
	v_mov_b32_e32 v8, v16
	v_mov_b32_e32 v9, v16
	v_mov_b32_e32 v10, v16
	v_mov_b32_e32 v11, v16
	v_mov_b32_e32 v12, v16
	v_mov_b32_e32 v13, v16
	v_mov_b32_e32 v14, v16
	v_mov_b32_e32 v15, v16
	v_add_u32_e32 v246, 0xc000, v56
	s_mov_b64 s[10:11], 0xab94080
	v_lshl_add_u64 v[244:245], v[50:51], 0, s[0:1]
	v_lshl_add_u64 v[244:245], v[244:245], 0, s[10:11]
	v_readfirstlane_b32 s10, v246
	s_mov_b32 m0, s10
	s_nop 0
	global_load_lds_dwordx4 v[244:245], off
	v_add_u32_e32 v243, 0x2000, v246
	s_mov_b64 s[10:11], 0xaba0080
	v_lshl_add_u64 v[244:245], v[50:51], 0, s[0:1]
	v_lshl_add_u64 v[244:245], v[244:245], 0, s[10:11]
	v_readfirstlane_b32 s10, v243
	s_mov_b32 m0, s10
	s_nop 0
	global_load_lds_dwordx4 v[244:245], off
	v_add_u32_e32 v243, 0x4000, v246
	s_mov_b64 s[10:11], 0x6814080
	v_lshl_add_u64 v[244:245], v[48:49], 0, s[0:1]
	v_lshl_add_u64 v[244:245], v[244:245], 0, s[10:11]
	v_readfirstlane_b32 s10, v243
	s_mov_b32 m0, s10
	s_nop 0
	global_load_lds_dwordx4 v[244:245], off
	v_add_u32_e32 v243, 0x6000, v246
	s_mov_b64 s[10:11], 0x6820080
	v_lshl_add_u64 v[244:245], v[48:49], 0, s[0:1]
	v_lshl_add_u64 v[244:245], v[244:245], 0, s[10:11]
	v_readfirstlane_b32 s10, v243
	s_mov_b32 m0, s10
	s_nop 0
	global_load_lds_dwordx4 v[244:245], off
	v_add_u32_e32 v243, 0x8000, v246
	s_mov_b64 s[10:11], 0x682c080
	v_lshl_add_u64 v[244:245], v[48:49], 0, s[0:1]
	v_lshl_add_u64 v[244:245], v[244:245], 0, s[10:11]
	v_readfirstlane_b32 s10, v243
	s_mov_b32 m0, s10
	s_nop 0
	global_load_lds_dwordx4 v[244:245], off
	v_add_u32_e32 v243, 0xa000, v246
	s_mov_b64 s[10:11], 0x6838080
	v_lshl_add_u64 v[244:245], v[48:49], 0, s[0:1]
	v_lshl_add_u64 v[244:245], v[244:245], 0, s[10:11]
	v_readfirstlane_b32 s10, v243
	s_mov_b32 m0, s10
	s_nop 0
	global_load_lds_dwordx4 v[244:245], off
	s_add_u32 s0, s0, 0x80
	s_addc_u32 s1, s1, 0
	s_waitcnt vmcnt(6) lgkmcnt(0)
	s_barrier
	v_mov_b32_e32 v184, v62
	v_mov_b32_e32 v154, v61
	v_add_u32_e32 v246, 0x18000, v56
	v_add_u32_e32 v181, v184, v59
	ds_read_b128 v[64:67], v181 offset:0x0
	ds_read_b128 v[68:71], v181 offset:0x1000
	ds_read_b128 v[72:75], v181 offset:0x2000
	ds_read_b128 v[76:79], v181 offset:0x3000
	v_add_u32_e32 v181, v154, v59
	ds_read_b128 v[80:83], v181 offset:0
	v_add_u32_e32 v181, v184, v58
	ds_read_b128 v[84:87], v181 offset:0x0
	ds_read_b128 v[88:91], v181 offset:0x1000
	ds_read_b128 v[92:95], v181 offset:0x2000
	ds_read_b128 v[100:103], v181 offset:0x3000
	v_add_u32_e32 v181, v154, v58
	ds_read_b128 v[104:107], v181 offset:0
	s_waitcnt lgkmcnt(5)
	v_mfma_f32_32x32x16_bf16 v[16:31], v[64:67], v[80:83], v[16:31]
	s_mov_b64 s[10:11], 0xab94080
	v_lshl_add_u64 v[244:245], v[50:51], 0, s[0:1]
	v_lshl_add_u64 v[244:245], v[244:245], 0, s[10:11]
	v_readfirstlane_b32 s10, v246
	s_mov_b32 m0, s10
	s_nop 0
	global_load_lds_dwordx4 v[244:245], off
	v_mfma_f32_32x32x16_bf16 v[32:47], v[68:71], v[80:83], v[32:47]
	v_add_u32_e32 v243, 0x2000, v246
	s_mov_b64 s[10:11], 0xaba0080
	v_lshl_add_u64 v[244:245], v[50:51], 0, s[0:1]
	v_lshl_add_u64 v[244:245], v[244:245], 0, s[10:11]
	v_readfirstlane_b32 s10, v243
	s_mov_b32 m0, s10
	s_nop 0
	global_load_lds_dwordx4 v[244:245], off
	v_mfma_f32_32x32x16_bf16 v[0:15], v[72:75], v[80:83], v[0:15]
	v_add_u32_e32 v243, 0x4000, v246
	s_mov_b64 s[10:11], 0x6814080
	v_lshl_add_u64 v[244:245], v[48:49], 0, s[0:1]
	v_lshl_add_u64 v[244:245], v[244:245], 0, s[10:11]
	v_readfirstlane_b32 s10, v243
	s_mov_b32 m0, s10
	s_nop 0
	global_load_lds_dwordx4 v[244:245], off
	v_add_u32_e32 v181, v184, v57
	ds_read_b128 v[64:67], v181 offset:0x0
	ds_read_b128 v[68:71], v181 offset:0x1000
	ds_read_b128 v[72:75], v181 offset:0x2000
	ds_read_b128 v[76:79], v181 offset:0x3000
	v_add_u32_e32 v181, v154, v57
	ds_read_b128 v[80:83], v181 offset:0
	s_waitcnt lgkmcnt(5)
	v_mfma_f32_32x32x16_bf16 v[16:31], v[84:87], v[104:107], v[16:31]
	v_add_u32_e32 v243, 0x6000, v246
	s_mov_b64 s[10:11], 0x6820080
	v_lshl_add_u64 v[244:245], v[48:49], 0, s[0:1]
	v_lshl_add_u64 v[244:245], v[244:245], 0, s[10:11]
	v_readfirstlane_b32 s10, v243
	s_mov_b32 m0, s10
	s_nop 0
	global_load_lds_dwordx4 v[244:245], off
	v_mfma_f32_32x32x16_bf16 v[32:47], v[88:91], v[104:107], v[32:47]
	v_add_u32_e32 v243, 0x8000, v246
	s_mov_b64 s[10:11], 0x682c080
	v_lshl_add_u64 v[244:245], v[48:49], 0, s[0:1]
	v_lshl_add_u64 v[244:245], v[244:245], 0, s[10:11]
	v_readfirstlane_b32 s10, v243
	s_mov_b32 m0, s10
	s_nop 0
	global_load_lds_dwordx4 v[244:245], off
	v_mfma_f32_32x32x16_bf16 v[0:15], v[92:95], v[104:107], v[0:15]
	v_add_u32_e32 v243, 0xa000, v246
	s_mov_b64 s[10:11], 0x6838080
	v_lshl_add_u64 v[244:245], v[48:49], 0, s[0:1]
	v_lshl_add_u64 v[244:245], v[244:245], 0, s[10:11]
	v_readfirstlane_b32 s10, v243
	s_mov_b32 m0, s10
	s_nop 0
	global_load_lds_dwordx4 v[244:245], off
	v_add_u32_e32 v181, v184, v55
	ds_read_b128 v[84:87], v181 offset:0x0
	ds_read_b128 v[88:91], v181 offset:0x1000
	ds_read_b128 v[92:95], v181 offset:0x2000
	ds_read_b128 v[100:103], v181 offset:0x3000
	v_add_u32_e32 v181, v154, v55
	ds_read_b128 v[104:107], v181 offset:0
	s_waitcnt lgkmcnt(5)
	v_mfma_f32_32x32x16_bf16 v[16:31], v[64:67], v[80:83], v[16:31]
	v_mfma_f32_32x32x16_bf16 v[32:47], v[68:71], v[80:83], v[32:47]
	v_mfma_f32_32x32x16_bf16 v[0:15], v[72:75], v[80:83], v[0:15]
	s_waitcnt lgkmcnt(0)
	v_mfma_f32_32x32x16_bf16 v[16:31], v[84:87], v[104:107], v[16:31]
	v_mfma_f32_32x32x16_bf16 v[32:47], v[88:91], v[104:107], v[32:47]
	v_mfma_f32_32x32x16_bf16 v[0:15], v[92:95], v[104:107], v[0:15]
	s_add_u32 s0, s0, 0x80
	s_addc_u32 s1, s1, 0
	s_waitcnt vmcnt(6) lgkmcnt(0)
	s_barrier
	v_add_u32_e32 v184, 0xc000, v62
	v_add_u32_e32 v154, 0xc000, v61
	v_mov_b32_e32 v246, v56
	v_add_u32_e32 v181, v184, v59
	ds_read_b128 v[64:67], v181 offset:0x0
	ds_read_b128 v[68:71], v181 offset:0x1000
	ds_read_b128 v[72:75], v181 offset:0x2000
	ds_read_b128 v[76:79], v181 offset:0x3000
	v_add_u32_e32 v181, v154, v59
	ds_read_b128 v[80:83], v181 offset:0
	v_add_u32_e32 v181, v184, v58
	ds_read_b128 v[84:87], v181 offset:0x0
	ds_read_b128 v[88:91], v181 offset:0x1000
	ds_read_b128 v[92:95], v181 offset:0x2000
	ds_read_b128 v[100:103], v181 offset:0x3000
	v_add_u32_e32 v181, v154, v58
	ds_read_b128 v[104:107], v181 offset:0
	s_waitcnt lgkmcnt(5)
	v_mfma_f32_32x32x16_bf16 v[16:31], v[64:67], v[80:83], v[16:31]
	s_mov_b64 s[10:11], 0xab94080
	v_lshl_add_u64 v[244:245], v[50:51], 0, s[0:1]
	v_lshl_add_u64 v[244:245], v[244:245], 0, s[10:11]
	v_readfirstlane_b32 s10, v246
	s_mov_b32 m0, s10
	s_nop 0
	global_load_lds_dwordx4 v[244:245], off
	v_mfma_f32_32x32x16_bf16 v[32:47], v[68:71], v[80:83], v[32:47]
	v_add_u32_e32 v243, 0x2000, v246
	s_mov_b64 s[10:11], 0xaba0080
	v_lshl_add_u64 v[244:245], v[50:51], 0, s[0:1]
	v_lshl_add_u64 v[244:245], v[244:245], 0, s[10:11]
	v_readfirstlane_b32 s10, v243
	s_mov_b32 m0, s10
	s_nop 0
	global_load_lds_dwordx4 v[244:245], off
	v_mfma_f32_32x32x16_bf16 v[0:15], v[72:75], v[80:83], v[0:15]
	v_add_u32_e32 v243, 0x4000, v246
	s_mov_b64 s[10:11], 0x6814080
	v_lshl_add_u64 v[244:245], v[48:49], 0, s[0:1]
	v_lshl_add_u64 v[244:245], v[244:245], 0, s[10:11]
	v_readfirstlane_b32 s10, v243
	s_mov_b32 m0, s10
	s_nop 0
	global_load_lds_dwordx4 v[244:245], off
	v_add_u32_e32 v181, v184, v57
	ds_read_b128 v[64:67], v181 offset:0x0
	ds_read_b128 v[68:71], v181 offset:0x1000
	ds_read_b128 v[72:75], v181 offset:0x2000
	ds_read_b128 v[76:79], v181 offset:0x3000
	v_add_u32_e32 v181, v154, v57
	ds_read_b128 v[80:83], v181 offset:0
	s_waitcnt lgkmcnt(5)
	v_mfma_f32_32x32x16_bf16 v[16:31], v[84:87], v[104:107], v[16:31]
	v_add_u32_e32 v243, 0x6000, v246
	s_mov_b64 s[10:11], 0x6820080
	v_lshl_add_u64 v[244:245], v[48:49], 0, s[0:1]
	v_lshl_add_u64 v[244:245], v[244:245], 0, s[10:11]
	v_readfirstlane_b32 s10, v243
	s_mov_b32 m0, s10
	s_nop 0
	global_load_lds_dwordx4 v[244:245], off
	v_mfma_f32_32x32x16_bf16 v[32:47], v[88:91], v[104:107], v[32:47]
	v_add_u32_e32 v243, 0x8000, v246
	s_mov_b64 s[10:11], 0x682c080
	v_lshl_add_u64 v[244:245], v[48:49], 0, s[0:1]
	v_lshl_add_u64 v[244:245], v[244:245], 0, s[10:11]
	v_readfirstlane_b32 s10, v243
	s_mov_b32 m0, s10
	s_nop 0
	global_load_lds_dwordx4 v[244:245], off
	v_mfma_f32_32x32x16_bf16 v[0:15], v[92:95], v[104:107], v[0:15]
	v_add_u32_e32 v243, 0xa000, v246
	s_mov_b64 s[10:11], 0x6838080
	v_lshl_add_u64 v[244:245], v[48:49], 0, s[0:1]
	v_lshl_add_u64 v[244:245], v[244:245], 0, s[10:11]
	v_readfirstlane_b32 s10, v243
	s_mov_b32 m0, s10
	s_nop 0
	global_load_lds_dwordx4 v[244:245], off
	v_add_u32_e32 v181, v184, v55
	ds_read_b128 v[84:87], v181 offset:0x0
	ds_read_b128 v[88:91], v181 offset:0x1000
	ds_read_b128 v[92:95], v181 offset:0x2000
	ds_read_b128 v[100:103], v181 offset:0x3000
	v_add_u32_e32 v181, v154, v55
	ds_read_b128 v[104:107], v181 offset:0
	s_waitcnt lgkmcnt(5)
	v_mfma_f32_32x32x16_bf16 v[16:31], v[64:67], v[80:83], v[16:31]
	v_mfma_f32_32x32x16_bf16 v[32:47], v[68:71], v[80:83], v[32:47]
	v_mfma_f32_32x32x16_bf16 v[0:15], v[72:75], v[80:83], v[0:15]
	s_waitcnt lgkmcnt(0)
	v_mfma_f32_32x32x16_bf16 v[16:31], v[84:87], v[104:107], v[16:31]
	v_mfma_f32_32x32x16_bf16 v[32:47], v[88:91], v[104:107], v[32:47]
	v_mfma_f32_32x32x16_bf16 v[0:15], v[92:95], v[104:107], v[0:15]
	s_add_u32 s0, s0, 0x80
	s_addc_u32 s1, s1, 0
	s_waitcnt vmcnt(6) lgkmcnt(0)
	s_barrier
	v_add_u32_e32 v184, 0x18000, v62
	v_add_u32_e32 v154, 0x18000, v61
	v_add_u32_e32 v246, 0xc000, v56
	v_add_u32_e32 v181, v184, v59
	ds_read_b128 v[64:67], v181 offset:0x0
	ds_read_b128 v[68:71], v181 offset:0x1000
	ds_read_b128 v[72:75], v181 offset:0x2000
	ds_read_b128 v[76:79], v181 offset:0x3000
	v_add_u32_e32 v181, v154, v59
	ds_read_b128 v[80:83], v181 offset:0
	v_add_u32_e32 v181, v184, v58
	ds_read_b128 v[84:87], v181 offset:0x0
	ds_read_b128 v[88:91], v181 offset:0x1000
	ds_read_b128 v[92:95], v181 offset:0x2000
	ds_read_b128 v[100:103], v181 offset:0x3000
	v_add_u32_e32 v181, v154, v58
	ds_read_b128 v[104:107], v181 offset:0
	s_waitcnt lgkmcnt(5)
	v_mfma_f32_32x32x16_bf16 v[16:31], v[64:67], v[80:83], v[16:31]
	s_mov_b64 s[10:11], 0xab94080
	v_lshl_add_u64 v[244:245], v[50:51], 0, s[0:1]
	v_lshl_add_u64 v[244:245], v[244:245], 0, s[10:11]
	v_readfirstlane_b32 s10, v246
	s_mov_b32 m0, s10
	s_nop 0
	global_load_lds_dwordx4 v[244:245], off
	v_mfma_f32_32x32x16_bf16 v[32:47], v[68:71], v[80:83], v[32:47]
	v_add_u32_e32 v243, 0x2000, v246
	s_mov_b64 s[10:11], 0xaba0080
	v_lshl_add_u64 v[244:245], v[50:51], 0, s[0:1]
	v_lshl_add_u64 v[244:245], v[244:245], 0, s[10:11]
	v_readfirstlane_b32 s10, v243
	s_mov_b32 m0, s10
	s_nop 0
	global_load_lds_dwordx4 v[244:245], off
	v_mfma_f32_32x32x16_bf16 v[0:15], v[72:75], v[80:83], v[0:15]
	v_add_u32_e32 v243, 0x4000, v246
	s_mov_b64 s[10:11], 0x6814080
	v_lshl_add_u64 v[244:245], v[48:49], 0, s[0:1]
	v_lshl_add_u64 v[244:245], v[244:245], 0, s[10:11]
	v_readfirstlane_b32 s10, v243
	s_mov_b32 m0, s10
	s_nop 0
	global_load_lds_dwordx4 v[244:245], off
	v_add_u32_e32 v181, v184, v57
	ds_read_b128 v[64:67], v181 offset:0x0
	ds_read_b128 v[68:71], v181 offset:0x1000
	ds_read_b128 v[72:75], v181 offset:0x2000
	ds_read_b128 v[76:79], v181 offset:0x3000
	v_add_u32_e32 v181, v154, v57
	ds_read_b128 v[80:83], v181 offset:0
	s_waitcnt lgkmcnt(5)
	v_mfma_f32_32x32x16_bf16 v[16:31], v[84:87], v[104:107], v[16:31]
	v_add_u32_e32 v243, 0x6000, v246
	s_mov_b64 s[10:11], 0x6820080
	v_lshl_add_u64 v[244:245], v[48:49], 0, s[0:1]
	v_lshl_add_u64 v[244:245], v[244:245], 0, s[10:11]
	v_readfirstlane_b32 s10, v243
	s_mov_b32 m0, s10
	s_nop 0
	global_load_lds_dwordx4 v[244:245], off
	v_mfma_f32_32x32x16_bf16 v[32:47], v[88:91], v[104:107], v[32:47]
	v_add_u32_e32 v243, 0x8000, v246
	s_mov_b64 s[10:11], 0x682c080
	v_lshl_add_u64 v[244:245], v[48:49], 0, s[0:1]
	v_lshl_add_u64 v[244:245], v[244:245], 0, s[10:11]
	v_readfirstlane_b32 s10, v243
	s_mov_b32 m0, s10
	s_nop 0
	global_load_lds_dwordx4 v[244:245], off
	v_mfma_f32_32x32x16_bf16 v[0:15], v[92:95], v[104:107], v[0:15]
	v_add_u32_e32 v243, 0xa000, v246
	s_mov_b64 s[10:11], 0x6838080
	v_lshl_add_u64 v[244:245], v[48:49], 0, s[0:1]
	v_lshl_add_u64 v[244:245], v[244:245], 0, s[10:11]
	v_readfirstlane_b32 s10, v243
	s_mov_b32 m0, s10
	s_nop 0
	global_load_lds_dwordx4 v[244:245], off
	v_add_u32_e32 v181, v184, v55
	ds_read_b128 v[84:87], v181 offset:0x0
	ds_read_b128 v[88:91], v181 offset:0x1000
	ds_read_b128 v[92:95], v181 offset:0x2000
	ds_read_b128 v[100:103], v181 offset:0x3000
	v_add_u32_e32 v181, v154, v55
	ds_read_b128 v[104:107], v181 offset:0
	s_waitcnt lgkmcnt(5)
	v_mfma_f32_32x32x16_bf16 v[16:31], v[64:67], v[80:83], v[16:31]
	v_mfma_f32_32x32x16_bf16 v[32:47], v[68:71], v[80:83], v[32:47]
	v_mfma_f32_32x32x16_bf16 v[0:15], v[72:75], v[80:83], v[0:15]
	s_waitcnt lgkmcnt(0)
	v_mfma_f32_32x32x16_bf16 v[16:31], v[84:87], v[104:107], v[16:31]
	v_mfma_f32_32x32x16_bf16 v[32:47], v[88:91], v[104:107], v[32:47]
	v_mfma_f32_32x32x16_bf16 v[0:15], v[92:95], v[104:107], v[0:15]
	s_add_u32 s0, s0, 0x80
	s_addc_u32 s1, s1, 0
	s_waitcnt vmcnt(6) lgkmcnt(0)
	s_barrier
	v_mov_b32_e32 v184, v62
	v_mov_b32_e32 v154, v61
	v_add_u32_e32 v246, 0x18000, v56
	v_add_u32_e32 v181, v184, v59
	ds_read_b128 v[64:67], v181 offset:0x0
	ds_read_b128 v[68:71], v181 offset:0x1000
	ds_read_b128 v[72:75], v181 offset:0x2000
	ds_read_b128 v[76:79], v181 offset:0x3000
	v_add_u32_e32 v181, v154, v59
	ds_read_b128 v[80:83], v181 offset:0
	v_add_u32_e32 v181, v184, v58
	ds_read_b128 v[84:87], v181 offset:0x0
	ds_read_b128 v[88:91], v181 offset:0x1000
	ds_read_b128 v[92:95], v181 offset:0x2000
	ds_read_b128 v[100:103], v181 offset:0x3000
	v_add_u32_e32 v181, v154, v58
	ds_read_b128 v[104:107], v181 offset:0
	s_waitcnt lgkmcnt(5)
	v_mfma_f32_32x32x16_bf16 v[16:31], v[64:67], v[80:83], v[16:31]
	s_mov_b64 s[10:11], 0xab94080
	v_lshl_add_u64 v[244:245], v[50:51], 0, s[0:1]
	v_lshl_add_u64 v[244:245], v[244:245], 0, s[10:11]
	v_readfirstlane_b32 s10, v246
	s_mov_b32 m0, s10
	s_nop 0
	global_load_lds_dwordx4 v[244:245], off
	v_mfma_f32_32x32x16_bf16 v[32:47], v[68:71], v[80:83], v[32:47]
	v_add_u32_e32 v243, 0x2000, v246
	s_mov_b64 s[10:11], 0xaba0080
	v_lshl_add_u64 v[244:245], v[50:51], 0, s[0:1]
	v_lshl_add_u64 v[244:245], v[244:245], 0, s[10:11]
	v_readfirstlane_b32 s10, v243
	s_mov_b32 m0, s10
	s_nop 0
	global_load_lds_dwordx4 v[244:245], off
	v_mfma_f32_32x32x16_bf16 v[0:15], v[72:75], v[80:83], v[0:15]
	v_add_u32_e32 v243, 0x4000, v246
	s_mov_b64 s[10:11], 0x6814080
	v_lshl_add_u64 v[244:245], v[48:49], 0, s[0:1]
	v_lshl_add_u64 v[244:245], v[244:245], 0, s[10:11]
	v_readfirstlane_b32 s10, v243
	s_mov_b32 m0, s10
	s_nop 0
	global_load_lds_dwordx4 v[244:245], off
	v_add_u32_e32 v181, v184, v57
	ds_read_b128 v[64:67], v181 offset:0x0
	ds_read_b128 v[68:71], v181 offset:0x1000
	ds_read_b128 v[72:75], v181 offset:0x2000
	ds_read_b128 v[76:79], v181 offset:0x3000
	v_add_u32_e32 v181, v154, v57
	ds_read_b128 v[80:83], v181 offset:0
	s_waitcnt lgkmcnt(5)
	v_mfma_f32_32x32x16_bf16 v[16:31], v[84:87], v[104:107], v[16:31]
	v_add_u32_e32 v243, 0x6000, v246
	s_mov_b64 s[10:11], 0x6820080
	v_lshl_add_u64 v[244:245], v[48:49], 0, s[0:1]
	v_lshl_add_u64 v[244:245], v[244:245], 0, s[10:11]
	v_readfirstlane_b32 s10, v243
	s_mov_b32 m0, s10
	s_nop 0
	global_load_lds_dwordx4 v[244:245], off
	v_mfma_f32_32x32x16_bf16 v[32:47], v[88:91], v[104:107], v[32:47]
	v_add_u32_e32 v243, 0x8000, v246
	s_mov_b64 s[10:11], 0x682c080
	v_lshl_add_u64 v[244:245], v[48:49], 0, s[0:1]
	v_lshl_add_u64 v[244:245], v[244:245], 0, s[10:11]
	v_readfirstlane_b32 s10, v243
	s_mov_b32 m0, s10
	s_nop 0
	global_load_lds_dwordx4 v[244:245], off
	v_mfma_f32_32x32x16_bf16 v[0:15], v[92:95], v[104:107], v[0:15]
	v_add_u32_e32 v243, 0xa000, v246
	s_mov_b64 s[10:11], 0x6838080
	v_lshl_add_u64 v[244:245], v[48:49], 0, s[0:1]
	v_lshl_add_u64 v[244:245], v[244:245], 0, s[10:11]
	v_readfirstlane_b32 s10, v243
	s_mov_b32 m0, s10
	s_nop 0
	global_load_lds_dwordx4 v[244:245], off
	v_add_u32_e32 v181, v184, v55
	ds_read_b128 v[84:87], v181 offset:0x0
	ds_read_b128 v[88:91], v181 offset:0x1000
	ds_read_b128 v[92:95], v181 offset:0x2000
	ds_read_b128 v[100:103], v181 offset:0x3000
	v_add_u32_e32 v181, v154, v55
	ds_read_b128 v[104:107], v181 offset:0
	s_waitcnt lgkmcnt(5)
	v_mfma_f32_32x32x16_bf16 v[16:31], v[64:67], v[80:83], v[16:31]
	v_mfma_f32_32x32x16_bf16 v[32:47], v[68:71], v[80:83], v[32:47]
	v_mfma_f32_32x32x16_bf16 v[0:15], v[72:75], v[80:83], v[0:15]
	s_waitcnt lgkmcnt(0)
	v_mfma_f32_32x32x16_bf16 v[16:31], v[84:87], v[104:107], v[16:31]
	v_mfma_f32_32x32x16_bf16 v[32:47], v[88:91], v[104:107], v[32:47]
	v_mfma_f32_32x32x16_bf16 v[0:15], v[92:95], v[104:107], v[0:15]
	s_add_u32 s0, s0, 0x80
	s_addc_u32 s1, s1, 0
	s_waitcnt vmcnt(6) lgkmcnt(0)
	s_barrier
	v_add_u32_e32 v184, 0xc000, v62
	v_add_u32_e32 v154, 0xc000, v61
	v_add_u32_e32 v181, v184, v59
	ds_read_b128 v[64:67], v181 offset:0x0
	ds_read_b128 v[68:71], v181 offset:0x1000
	ds_read_b128 v[72:75], v181 offset:0x2000
	ds_read_b128 v[76:79], v181 offset:0x3000
	v_add_u32_e32 v181, v154, v59
	ds_read_b128 v[80:83], v181 offset:0
	v_add_u32_e32 v181, v184, v58
	ds_read_b128 v[84:87], v181 offset:0x0
	ds_read_b128 v[88:91], v181 offset:0x1000
	ds_read_b128 v[92:95], v181 offset:0x2000
	ds_read_b128 v[100:103], v181 offset:0x3000
	v_add_u32_e32 v181, v154, v58
	ds_read_b128 v[104:107], v181 offset:0
	s_waitcnt lgkmcnt(5)
	v_mfma_f32_32x32x16_bf16 v[16:31], v[64:67], v[80:83], v[16:31]
	v_mfma_f32_32x32x16_bf16 v[32:47], v[68:71], v[80:83], v[32:47]
	v_mfma_f32_32x32x16_bf16 v[0:15], v[72:75], v[80:83], v[0:15]
	v_add_u32_e32 v181, v184, v57
	ds_read_b128 v[64:67], v181 offset:0x0
	ds_read_b128 v[68:71], v181 offset:0x1000
	ds_read_b128 v[72:75], v181 offset:0x2000
	ds_read_b128 v[76:79], v181 offset:0x3000
	v_add_u32_e32 v181, v154, v57
	ds_read_b128 v[80:83], v181 offset:0
	s_waitcnt lgkmcnt(5)
	v_mfma_f32_32x32x16_bf16 v[16:31], v[84:87], v[104:107], v[16:31]
	v_mfma_f32_32x32x16_bf16 v[32:47], v[88:91], v[104:107], v[32:47]
	v_mfma_f32_32x32x16_bf16 v[0:15], v[92:95], v[104:107], v[0:15]
	v_add_u32_e32 v181, v184, v55
	ds_read_b128 v[84:87], v181 offset:0x0
	ds_read_b128 v[88:91], v181 offset:0x1000
	ds_read_b128 v[92:95], v181 offset:0x2000
	ds_read_b128 v[100:103], v181 offset:0x3000
	v_add_u32_e32 v181, v154, v55
	ds_read_b128 v[104:107], v181 offset:0
	s_waitcnt lgkmcnt(5)
	v_mfma_f32_32x32x16_bf16 v[16:31], v[64:67], v[80:83], v[16:31]
	v_mfma_f32_32x32x16_bf16 v[32:47], v[68:71], v[80:83], v[32:47]
	v_mfma_f32_32x32x16_bf16 v[0:15], v[72:75], v[80:83], v[0:15]
	s_waitcnt lgkmcnt(0)
	v_mfma_f32_32x32x16_bf16 v[16:31], v[84:87], v[104:107], v[16:31]
	v_mfma_f32_32x32x16_bf16 v[32:47], v[88:91], v[104:107], v[32:47]
	v_mfma_f32_32x32x16_bf16 v[0:15], v[92:95], v[104:107], v[0:15]
	s_waitcnt vmcnt(0) lgkmcnt(0)
	s_barrier
	v_add_u32_e32 v184, 0x18000, v62
	v_add_u32_e32 v154, 0x18000, v61
	v_add_u32_e32 v181, v184, v59
	ds_read_b128 v[64:67], v181 offset:0x0
	ds_read_b128 v[68:71], v181 offset:0x1000
	ds_read_b128 v[72:75], v181 offset:0x2000
	ds_read_b128 v[76:79], v181 offset:0x3000
	v_add_u32_e32 v181, v154, v59
	ds_read_b128 v[80:83], v181 offset:0
	v_add_u32_e32 v181, v184, v58
	ds_read_b128 v[84:87], v181 offset:0x0
	ds_read_b128 v[88:91], v181 offset:0x1000
	ds_read_b128 v[92:95], v181 offset:0x2000
	ds_read_b128 v[100:103], v181 offset:0x3000
	v_add_u32_e32 v181, v154, v58
	ds_read_b128 v[104:107], v181 offset:0
	s_waitcnt lgkmcnt(5)
	v_mfma_f32_32x32x16_bf16 v[16:31], v[64:67], v[80:83], v[16:31]
	v_mfma_f32_32x32x16_bf16 v[32:47], v[68:71], v[80:83], v[32:47]
	v_mfma_f32_32x32x16_bf16 v[0:15], v[72:75], v[80:83], v[0:15]
	v_add_u32_e32 v181, v184, v57
	ds_read_b128 v[64:67], v181 offset:0x0
	ds_read_b128 v[68:71], v181 offset:0x1000
	ds_read_b128 v[72:75], v181 offset:0x2000
	ds_read_b128 v[76:79], v181 offset:0x3000
	v_add_u32_e32 v181, v154, v57
	ds_read_b128 v[80:83], v181 offset:0
	s_waitcnt lgkmcnt(5)
	v_mfma_f32_32x32x16_bf16 v[16:31], v[84:87], v[104:107], v[16:31]
	v_mfma_f32_32x32x16_bf16 v[32:47], v[88:91], v[104:107], v[32:47]
	v_mfma_f32_32x32x16_bf16 v[0:15], v[92:95], v[104:107], v[0:15]
	v_add_u32_e32 v181, v184, v55
	ds_read_b128 v[84:87], v181 offset:0x0
	ds_read_b128 v[88:91], v181 offset:0x1000
	ds_read_b128 v[92:95], v181 offset:0x2000
	ds_read_b128 v[100:103], v181 offset:0x3000
	v_add_u32_e32 v181, v154, v55
	ds_read_b128 v[104:107], v181 offset:0
	s_waitcnt lgkmcnt(5)
	v_mfma_f32_32x32x16_bf16 v[16:31], v[64:67], v[80:83], v[16:31]
	v_mfma_f32_32x32x16_bf16 v[32:47], v[68:71], v[80:83], v[32:47]
	v_mfma_f32_32x32x16_bf16 v[0:15], v[72:75], v[80:83], v[0:15]
	s_waitcnt lgkmcnt(0)
	v_mfma_f32_32x32x16_bf16 v[16:31], v[84:87], v[104:107], v[16:31]
	v_mfma_f32_32x32x16_bf16 v[32:47], v[88:91], v[104:107], v[32:47]
	v_mfma_f32_32x32x16_bf16 v[0:15], v[92:95], v[104:107], v[0:15]
	v_or_b32_e32 v48, s2, v52
	v_lshrrev_b32_e32 v100, 3, v53
	v_add_u32_e32 v80, v54, v48
	v_and_b32_e32 v99, 4, v100
	s_barrier
	v_ashrrev_i32_e32 v81, 31, v80
	v_lshl_add_u64 v[48:49], v[80:81], 2, s[64:65]
	s_mov_b32 s0, 0xc000
	v_add_co_u32_e32 v50, vcc, s0, v48
	s_mov_b32 s0, 0x18000
	s_nop 0
	v_addc_co_u32_e32 v51, vcc, 0, v49, vcc
	v_add_co_u32_e32 v52, vcc, s0, v48
	v_lshlrev_b32_e32 v84, 2, v99
	s_nop 0
	v_addc_co_u32_e32 v53, vcc, 0, v49, vcc
	global_load_dword v81, v[48:49], off
	global_load_dword v82, v[50:51], off
	global_load_dword v83, v[52:53], off
	global_load_dwordx4 v[76:79], v84, s[42:43]
	global_load_dwordx4 v[72:75], v84, s[42:43] offset:32
	global_load_dwordx4 v[68:71], v84, s[42:43] offset:64
	global_load_dwordx4 v[64:67], v84, s[42:43] offset:96
	global_load_dwordx4 v[60:63], v84, s[42:43] offset:128
	global_load_dwordx4 v[56:59], v84, s[42:43] offset:160
	global_load_dwordx4 v[52:55], v84, s[42:43] offset:192
	global_load_dwordx4 v[48:51], v84, s[42:43] offset:224
	global_load_dwordx4 v[102:105], v84, s[42:43] offset:256
	global_load_dwordx4 v[106:109], v84, s[42:43] offset:288
	global_load_dwordx4 v[110:113], v84, s[42:43] offset:320
	global_load_dwordx4 v[114:117], v84, s[42:43] offset:352
	s_mov_b32 s0, 0x800000
	s_waitcnt vmcnt(14)
	v_add_f32_e32 v81, 0, v81
	s_waitcnt vmcnt(13)
	v_add_f32_e32 v81, v81, v82
	s_waitcnt vmcnt(12)
	v_add_f32_e32 v81, v81, v83
	v_fmamk_f32 v81, v81, 0x3b2aaaab, v163
	v_mul_f32_e32 v82, 0x4b800000, v81
	v_cmp_gt_f32_e32 vcc, s0, v81
	s_nop 1
	v_cndmask_b32_e32 v81, v81, v82, vcc
	v_rsq_f32_e32 v81, v81
	s_nop 0
	v_mul_f32_e32 v82, 0x45800000, v81
	v_cndmask_b32_e32 v118, v81, v82, vcc
	v_pk_mul_f32 v[96:97], v[16:17], v[118:119] op_sel_hi:[1,0]
	v_pk_mul_f32 v[94:95], v[18:19], v[118:119] op_sel_hi:[1,0]
	v_pk_mul_f32 v[86:87], v[26:27], v[118:119] op_sel_hi:[1,0]
	v_pk_mul_f32 v[26:27], v[36:37], v[118:119] op_sel_hi:[1,0]
	v_pk_mul_f32 v[36:37], v[14:15], v[118:119] op_sel_hi:[1,0]
	v_pk_mul_f32 v[14:15], v[0:1], v[118:119] op_sel_hi:[1,0]
	v_pk_mul_f32 v[0:1], v[96:97], v[96:97]
	v_pk_mul_f32 v[88:89], v[24:25], v[118:119] op_sel_hi:[1,0]
	v_pk_mul_f32 v[24:25], v[38:39], v[118:119] op_sel_hi:[1,0]
	v_pk_mul_f32 v[38:39], v[12:13], v[118:119] op_sel_hi:[1,0]
	v_pk_mul_f32 v[12:13], v[94:95], v[94:95]
	v_add_f32_e32 v0, v0, v1
	v_pk_mul_f32 v[92:93], v[20:21], v[118:119] op_sel_hi:[1,0]
	v_add_f32_e32 v0, v12, v0
	v_pk_mul_f32 v[82:83], v[30:31], v[118:119] op_sel_hi:[1,0]
	v_pk_mul_f32 v[30:31], v[32:33], v[118:119] op_sel_hi:[1,0]
	v_pk_mul_f32 v[32:33], v[92:93], v[92:93]
	v_add_f32_e32 v0, v13, v0
	v_pk_mul_f32 v[90:91], v[22:23], v[118:119] op_sel_hi:[1,0]
	v_add_f32_e32 v0, v32, v0
	v_pk_mul_f32 v[84:85], v[28:29], v[118:119] op_sel_hi:[1,0]
	v_pk_mul_f32 v[28:29], v[34:35], v[118:119] op_sel_hi:[1,0]
	v_pk_mul_f32 v[34:35], v[90:91], v[90:91]
	v_add_f32_e32 v0, v33, v0
	v_add_f32_e32 v0, v34, v0
	v_pk_mul_f32 v[22:23], v[40:41], v[118:119] op_sel_hi:[1,0]
	v_pk_mul_f32 v[40:41], v[88:89], v[88:89]
	v_add_f32_e32 v0, v35, v0
	v_add_f32_e32 v0, v40, v0
	v_pk_mul_f32 v[20:21], v[42:43], v[118:119] op_sel_hi:[1,0]
	v_pk_mul_f32 v[42:43], v[86:87], v[86:87]
	v_add_f32_e32 v0, v41, v0
	v_add_f32_e32 v0, v42, v0
	v_pk_mul_f32 v[18:19], v[44:45], v[118:119] op_sel_hi:[1,0]
	v_pk_mul_f32 v[44:45], v[84:85], v[84:85]
	v_add_f32_e32 v0, v43, v0
	v_add_f32_e32 v0, v44, v0
	v_pk_mul_f32 v[16:17], v[46:47], v[118:119] op_sel_hi:[1,0]
	v_pk_mul_f32 v[46:47], v[82:83], v[82:83]
	v_add_f32_e32 v0, v45, v0
	v_add_f32_e32 v0, v46, v0
	v_mul_f32_e32 v81, v6, v118
	v_mul_f32_e32 v6, v7, v118
	v_pk_mul_f32 v[8:9], v[8:9], v[118:119] op_sel_hi:[1,0]
	v_pk_mul_f32 v[2:3], v[2:3], v[118:119] op_sel_hi:[1,0]
	v_pk_mul_f32 v[10:11], v[10:11], v[118:119] op_sel_hi:[1,0]
	v_pk_mul_f32 v[4:5], v[4:5], v[118:119] op_sel_hi:[1,0]
	v_pk_mul_f32 v[118:119], v[30:31], v[30:31]
	v_add_f32_e32 v0, v47, v0
	v_add_f32_e32 v0, v118, v0
	v_pk_mul_f32 v[120:121], v[28:29], v[28:29]
	v_add_f32_e32 v0, v119, v0
	v_add_f32_e32 v0, v120, v0
	v_pk_mul_f32 v[122:123], v[26:27], v[26:27]
	v_add_f32_e32 v0, v121, v0
	v_add_f32_e32 v0, v122, v0
	v_pk_mul_f32 v[124:125], v[24:25], v[24:25]
	v_add_f32_e32 v0, v123, v0
	v_add_f32_e32 v0, v124, v0
	v_pk_mul_f32 v[126:127], v[22:23], v[22:23]
	v_add_f32_e32 v0, v125, v0
	v_add_f32_e32 v0, v126, v0
	v_pk_mul_f32 v[130:131], v[20:21], v[20:21]
	v_add_f32_e32 v0, v127, v0
	v_add_f32_e32 v0, v130, v0
	v_pk_mul_f32 v[132:133], v[18:19], v[18:19]
	v_add_f32_e32 v0, v131, v0
	v_add_f32_e32 v0, v132, v0
	v_pk_mul_f32 v[134:135], v[16:17], v[16:17]
	v_add_f32_e32 v0, v133, v0
	v_add_f32_e32 v0, v134, v0
	v_pk_mul_f32 v[144:145], v[14:15], v[14:15]
	v_add_f32_e32 v0, v135, v0
	v_add_f32_e32 v0, v144, v0
	v_pk_mul_f32 v[148:149], v[2:3], v[2:3]
	v_add_f32_e32 v0, v145, v0
	v_add_f32_e32 v0, v148, v0
	v_pk_mul_f32 v[152:153], v[4:5], v[4:5]
	v_add_f32_e32 v0, v149, v0
	v_add_f32_e32 v0, v152, v0
	v_add_f32_e32 v0, v153, v0
	v_fmac_f32_e32 v0, v81, v81
	v_pk_mul_f32 v[146:147], v[8:9], v[8:9]
	v_fmac_f32_e32 v0, v6, v6
	v_add_f32_e32 v0, v146, v0
	v_pk_mul_f32 v[150:151], v[10:11], v[10:11]
	v_add_f32_e32 v0, v147, v0
	v_add_f32_e32 v0, v150, v0
	v_pk_mul_f32 v[182:183], v[38:39], v[38:39]
	v_add_f32_e32 v0, v151, v0
	v_add_f32_e32 v0, v182, v0
	v_pk_mul_f32 v[136:137], v[36:37], v[36:37]
	v_add_f32_e32 v0, v183, v0
	v_add_f32_e32 v0, v136, v0
	v_add_f32_e32 v0, v137, v0
	v_mov_b32_e32 v1, v0
	s_nop 1
	v_permlane32_swap_b32_e32 v0, v1
	v_add_f32_e32 v0, v0, v1
	v_fmamk_f32 v0, v0, 0x3c2aaaab, v163
	v_mul_f32_e32 v1, 0x4b800000, v0
	v_cmp_gt_f32_e32 vcc, s0, v0
	v_mov_b32_e32 v13, v37
	s_movk_i32 s0, 0xfff
	v_cndmask_b32_e32 v0, v0, v1, vcc
	v_rsq_f32_e32 v0, v0
	v_cmp_lt_i32_e64 s[0:1], s0, v80
	v_mul_f32_e32 v1, 0x45800000, v0
	v_cndmask_b32_e32 v0, v0, v1, vcc
	s_waitcnt vmcnt(3)
	v_pk_mul_f32 v[32:33], v[0:1], v[102:103] op_sel_hi:[0,1]
	v_pk_mul_f32 v[40:41], v[0:1], v[104:105] op_sel_hi:[0,1]
	s_waitcnt vmcnt(2)
	v_pk_mul_f32 v[42:43], v[0:1], v[106:107] op_sel_hi:[0,1]
	v_mul_f32_e32 v1, v0, v108
	v_mul_f32_e32 v12, v0, v109
	s_waitcnt vmcnt(0)
	v_mul_f32_e32 v7, v0, v117
	v_pk_mul_f32 v[44:45], v[0:1], v[110:111] op_sel_hi:[0,1]
	v_pk_mul_f32 v[12:13], v[12:13], v[6:7]
	v_pk_mul_f32 v[6:7], v[0:1], v[112:113] op_sel_hi:[0,1]
	v_pk_mul_f32 v[34:35], v[14:15], v[32:33]
	v_pk_mul_f32 v[32:33], v[2:3], v[40:41]
	v_pk_mul_f32 v[14:15], v[4:5], v[42:43]
	v_mul_f32_e32 v4, v81, v1
	v_pk_mul_f32 v[2:3], v[8:9], v[44:45]
	v_pk_mul_f32 v[8:9], v[10:11], v[6:7]
	v_pk_mul_f32 v[6:7], v[0:1], v[114:115] op_sel_hi:[0,1]
	v_mul_f32_e32 v1, v0, v116
	v_pk_mul_f32 v[6:7], v[38:39], v[6:7]
	v_mul_f32_e32 v10, v36, v1
	s_and_saveexec_b64 s[2:3], s[0:1]
	s_cbranch_execz .LBB0_491
	v_cvt_f32_ubyte0_e32 v11, v99
	v_mul_f32_e32 v11, 0xbfd49a78, v11
	v_exp_f32_e32 v11, v11
	v_bfe_u32 v5, v80, 6, 4
	v_cvt_f32_ubyte0_e32 v5, v5
	v_and_b32_e32 v1, 63, v80
	v_mul_f32_e32 v36, v11, v5
	v_mul_f32_e32 v37, 0.15915494, v36
	v_cos_f32_e32 v36, v37
	v_sin_f32_e32 v38, v37
	v_or_b32_e32 v37, 1, v99
	v_cvt_f32_ubyte0_e32 v37, v37
	v_mul_f32_e32 v37, 0xbfd49a78, v37
	v_exp_f32_e32 v42, v37
	v_cvt_f32_ubyte0_e32 v1, v1
	v_mul_f32_e32 v37, v42, v5
	v_mul_f32_e32 v39, 0.15915494, v37
	v_cos_f32_e32 v37, v39
	v_sin_f32_e32 v39, v39
	s_nop 0
	v_pk_mul_f32 v[40:41], v[38:39], v[2:3]
	v_pk_mul_f32 v[2:3], v[36:37], v[2:3]
	v_pk_fma_f32 v[40:41], v[36:37], v[34:35], v[40:41] neg_lo:[0,0,1] neg_hi:[0,0,1]
	v_pk_fma_f32 v[2:3], v[38:39], v[34:35], v[2:3]
	v_or_b32_e32 v34, 2, v99
	v_cvt_f32_ubyte0_e32 v34, v34
	v_mul_f32_e32 v34, 0xbfd49a78, v34
	v_exp_f32_e32 v43, v34
	s_nop 0
	v_mul_f32_e32 v34, v43, v5
	v_mul_f32_e32 v35, 0.15915494, v34
	v_cos_f32_e32 v34, v35
	v_sin_f32_e32 v36, v35
	v_or_b32_e32 v35, 3, v100
	v_cvt_f32_ubyte0_e32 v35, v35
	v_mul_f32_e32 v35, 0xbfd49a78, v35
	v_exp_f32_e32 v44, v35
	s_nop 0
	v_mul_f32_e32 v5, v44, v5
	v_mul_f32_e32 v5, 0.15915494, v5
	v_cos_f32_e32 v35, v5
	v_sin_f32_e32 v37, v5
	v_mul_f32_e32 v5, v11, v1
	v_mul_f32_e32 v5, 0.15915494, v5
	v_mov_b32_e32 v11, v13
	v_pk_mul_f32 v[38:39], v[36:37], v[8:9]
	v_pk_mul_f32 v[8:9], v[34:35], v[8:9]
	v_pk_fma_f32 v[38:39], v[34:35], v[32:33], v[38:39] neg_lo:[0,0,1] neg_hi:[0,0,1]
	v_pk_fma_f32 v[8:9], v[36:37], v[32:33], v[8:9]
	v_cos_f32_e32 v32, v5
	v_sin_f32_e32 v34, v5
	v_mul_f32_e32 v5, v42, v1
	v_mul_f32_e32 v5, 0.15915494, v5
	v_cos_f32_e32 v33, v5
	v_sin_f32_e32 v35, v5
	v_mul_f32_e32 v5, v43, v1
	v_mul_f32_e32 v1, v44, v1
	v_mul_f32_e32 v5, 0.15915494, v5
	v_pk_mul_f32 v[36:37], v[34:35], v[6:7]
	v_pk_mul_f32 v[6:7], v[32:33], v[6:7]
	v_mul_f32_e32 v1, 0.15915494, v1
	v_pk_fma_f32 v[36:37], v[32:33], v[14:15], v[36:37] neg_lo:[0,0,1] neg_hi:[0,0,1]
	v_pk_fma_f32 v[6:7], v[34:35], v[14:15], v[6:7]
	v_cos_f32_e32 v14, v5
	v_sin_f32_e32 v32, v5
	v_sin_f32_e32 v33, v1
	v_cos_f32_e32 v15, v1
	v_mul_f32_e32 v34, v14, v10
	v_mov_b32_e32 v5, v12
	v_pk_mul_f32 v[10:11], v[32:33], v[10:11]
	v_mul_f32_e32 v42, v32, v4
	v_pk_fma_f32 v[4:5], v[14:15], v[4:5], v[10:11] neg_lo:[0,0,1] neg_hi:[0,0,1]
	v_mov_b32_e32 v14, v33
	v_pk_mul_f32 v[10:11], v[14:15], v[12:13]
	v_mov_b32_e32 v32, v38
	v_mov_b32_e32 v43, v10
	v_mov_b32_e32 v35, v11
	v_pk_add_f32 v[10:11], v[42:43], v[34:35]
	v_mov_b32_e32 v34, v40
	v_mov_b32_e32 v35, v41
	v_mov_b32_e32 v33, v39
	v_mov_b32_e32 v14, v36
	v_mov_b32_e32 v15, v37
	v_mov_b32_e32 v12, v5
	v_mov_b32_e32 v13, v11

.LBB0_494:
	s_mul_hi_i32 s0, s8, 0x92492493
	s_add_i32 s0, s0, s8
	s_lshr_b32 s1, s0, 31
	s_ashr_i32 s0, s0, 6
	s_add_i32 s16, s0, s1
	s_mul_i32 s0, s16, 0x70
	s_sub_i32 s9, s8, s0
	s_cmpk_lt_i32 s9, 0x60
	s_cselect_b64 s[2:3], -1, 0
	s_cmpk_gt_i32 s9, 0x5f
	s_cselect_b64 s[0:1], -1, 0
	s_and_b64 s[10:11], s[2:3], exec
	s_cselect_b32 s13, s7, s5
	s_cselect_b32 s12, s6, s4
	s_lshl_b32 s9, s9, 7
	v_mov_b32_e32 v6, v155
	s_add_i32 s10, s9, 0xffffd000
	s_and_b64 s[2:3], s[2:3], exec
	v_ashrrev_i32_e32 v0, 6, v6
	v_lshrrev_b32_e32 v1, 31, v6
	v_add_u32_e32 v7, v0, v1
	s_cselect_b32 s9, s9, s10
	v_and_b32_e32 v1, 0x1fffffe, v7
	v_ashrrev_i32_e32 v2, 3, v6
	v_sub_u32_e32 v8, v0, v1
	v_lshrrev_b32_e32 v9, 4, v6
	v_add_u32_e32 v0, s9, v2
	v_xor_b32_e32 v3, v9, v6
	v_ashrrev_i32_e32 v1, 31, v0
	v_lshlrev_b64 v[0:1], 9, v[0:1]
	v_lshlrev_b32_e32 v3, 4, v3
	v_lshlrev_b32_e32 v72, 4, v6
	s_lshl_b32 s10, s16, 8
	v_lshl_add_u64 v[0:1], s[12:13], 0, v[0:1]
	v_and_b32_e32 v128, 0x70, v3
	v_readfirstlane_b32 s2, v72
	v_add_u32_e32 v10, 0x2000, v72
	v_lshl_add_u64 v[64:65], v[0:1], 0, v[128:129]
	v_add_u32_e32 v0, s10, v2
	s_mov_b32 m0, s2
	s_mov_b64 s[12:13], 0x8000
	v_readfirstlane_b32 s2, v10
	v_ashrrev_i32_e32 v1, 31, v0
	s_barrier
	global_load_lds_dwordx4 v[64:65], off
	v_lshl_add_u64 v[4:5], v[64:65], 0, s[12:13]
	s_mov_b32 m0, s2
	v_lshlrev_b64 v[0:1], 9, v[0:1]
	global_load_lds_dwordx4 v[4:5], off
	v_add_u32_e32 v4, 0x4000, v72
	v_lshl_add_u64 v[2:3], s[68:69], 0, v[0:1]
	v_readfirstlane_b32 s2, v4
	v_add_u32_e32 v10, 0x6000, v72
	v_lshl_add_u64 v[2:3], v[2:3], 0, v[128:129]
	s_mov_b32 m0, s2
	v_readfirstlane_b32 s2, v10
	global_load_lds_dwordx4 v[2:3], off
	v_lshl_add_u64 v[4:5], v[2:3], 0, s[12:13]
	s_mov_b32 m0, s2
	s_mov_b64 s[2:3], 0x10000
	v_add_u32_e32 v10, 0x8000, v72
	global_load_lds_dwordx4 v[4:5], off
	v_lshl_add_u64 v[4:5], v[2:3], 0, s[2:3]
	v_readfirstlane_b32 s2, v10
	s_mov_b32 m0, s2
	s_mov_b64 s[2:3], 0x18000
	global_load_lds_dwordx4 v[4:5], off
	v_add_u32_e32 v4, 0xa000, v72
	v_lshl_add_u64 v[2:3], v[2:3], 0, s[2:3]
	v_readfirstlane_b32 s2, v4
	s_mov_b32 m0, s2
	s_waitcnt vmcnt(0)
	v_bfe_u32 v87, v6, 5, 1
	global_load_lds_dwordx4 v[2:3], off
	v_lshrrev_b32_e32 v2, 1, v6
	v_bfe_u32 v3, v6, 1, 3
	v_bitop3_b32 v2, v87, v2, 7 bitop3:0x78
	v_lshlrev_b32_e32 v75, 4, v2
	v_bitop3_b32 v2, v87, v3, 2 bitop3:0x36
	v_and_b32_e32 v68, 31, v6
	v_lshlrev_b32_e32 v69, 7, v8
	v_lshlrev_b32_e32 v74, 4, v2
	v_bitop3_b32 v2, v87, v3, 4 bitop3:0x36
	v_or_b32_e32 v4, v69, v68
	v_lshlrev_b32_e32 v73, 4, v2
	v_bitop3_b32 v2, v87, v3, 6 bitop3:0x36
	v_lshlrev_b32_e32 v76, 7, v4
	v_lshlrev_b32_e32 v4, 4, v7
	s_movk_i32 s2, 0xffe0
	v_lshlrev_b32_e32 v71, 4, v2
	v_bitop3_b32 v2, v9, 7, v6 bitop3:0x48
	v_and_b32_e32 v70, 0xffffffe0, v4
	v_bfi_b32 v4, s2, v4, v6
	v_lshl_or_b32 v0, v2, 4, v0
	v_mov_b32_e32 v48, 0
	v_and_b32_e32 v94, 63, v6
	v_lshlrev_b32_e32 v77, 7, v4
	v_add_u32_e32 v78, 0x4000, v76
	v_lshl_add_u64 v[66:67], s[14:15], 0, v[0:1]
	s_mov_b32 s11, 0
	s_mov_b64 s[2:3], 0
	v_mov_b32_e32 v49, v48
	v_mov_b32_e32 v50, v48
	v_mov_b32_e32 v51, v48
	v_mov_b32_e32 v52, v48
	v_mov_b32_e32 v53, v48
	v_mov_b32_e32 v54, v48
	v_mov_b32_e32 v55, v48
	v_mov_b32_e32 v56, v48
	v_mov_b32_e32 v57, v48
	v_mov_b32_e32 v58, v48
	v_mov_b32_e32 v59, v48
	v_mov_b32_e32 v60, v48
	v_mov_b32_e32 v61, v48
	v_mov_b32_e32 v62, v48
	v_mov_b32_e32 v63, v48
	v_mov_b32_e32 v32, v48
	v_mov_b32_e32 v33, v48
	v_mov_b32_e32 v34, v48
	v_mov_b32_e32 v35, v48
	v_mov_b32_e32 v36, v48
	v_mov_b32_e32 v37, v48
	v_mov_b32_e32 v38, v48
	v_mov_b32_e32 v39, v48
	v_mov_b32_e32 v40, v48
	v_mov_b32_e32 v41, v48
	v_mov_b32_e32 v42, v48
	v_mov_b32_e32 v43, v48
	v_mov_b32_e32 v44, v48
	v_mov_b32_e32 v45, v48
	v_mov_b32_e32 v46, v48
	v_mov_b32_e32 v47, v48
	v_mov_b32_e32 v0, v48
	v_mov_b32_e32 v1, v48
	v_mov_b32_e32 v2, v48
	v_mov_b32_e32 v3, v48
	v_mov_b32_e32 v4, v48
	v_mov_b32_e32 v5, v48
	v_mov_b32_e32 v6, v48
	v_mov_b32_e32 v7, v48
	v_mov_b32_e32 v8, v48
	v_mov_b32_e32 v9, v48
	v_mov_b32_e32 v10, v48
	v_mov_b32_e32 v11, v48
	v_mov_b32_e32 v12, v48
	v_mov_b32_e32 v13, v48
	v_mov_b32_e32 v14, v48
	v_mov_b32_e32 v15, v48
	v_mov_b32_e32 v16, v48
	v_mov_b32_e32 v17, v48
	v_mov_b32_e32 v18, v48
	v_mov_b32_e32 v19, v48
	v_mov_b32_e32 v20, v48
	v_mov_b32_e32 v21, v48
	v_mov_b32_e32 v22, v48
	v_mov_b32_e32 v23, v48
	v_mov_b32_e32 v24, v48
	v_mov_b32_e32 v25, v48
	v_mov_b32_e32 v26, v48
	v_mov_b32_e32 v27, v48
	v_mov_b32_e32 v28, v48
	v_mov_b32_e32 v29, v48
	v_mov_b32_e32 v30, v48
	v_mov_b32_e32 v31, v48
	s_mov_b64 s[16:17], 0x80
	v_add_u32_e32 v246, 0xc000, v72
	v_lshl_add_u64 v[244:245], v[64:65], 0, s[2:3]
	v_lshl_add_u64 v[244:245], v[244:245], 0, s[16:17]
	v_readfirstlane_b32 s12, v246
	s_mov_b32 m0, s12
	s_nop 0
	global_load_lds_dwordx4 v[244:245], off
	v_add_u32_e32 v243, 0x2000, v246
	s_mov_b64 s[12:13], 0x8080
	v_lshl_add_u64 v[244:245], v[64:65], 0, s[2:3]
	v_lshl_add_u64 v[244:245], v[244:245], 0, s[12:13]
	v_readfirstlane_b32 s12, v243
	s_mov_b32 m0, s12
	s_nop 0
	global_load_lds_dwordx4 v[244:245], off
	v_add_u32_e32 v243, 0x4000, v246
	s_mov_b64 s[12:13], 0x6994080
	v_lshl_add_u64 v[244:245], v[66:67], 0, s[2:3]
	v_lshl_add_u64 v[244:245], v[244:245], 0, s[12:13]
	v_readfirstlane_b32 s12, v243
	s_mov_b32 m0, s12
	s_nop 0
	global_load_lds_dwordx4 v[244:245], off
	v_add_u32_e32 v243, 0x6000, v246
	s_mov_b64 s[12:13], 0x699c080
	v_lshl_add_u64 v[244:245], v[66:67], 0, s[2:3]
	v_lshl_add_u64 v[244:245], v[244:245], 0, s[12:13]
	v_readfirstlane_b32 s12, v243
	s_mov_b32 m0, s12
	s_nop 0
	global_load_lds_dwordx4 v[244:245], off
	v_add_u32_e32 v243, 0x8000, v246
	s_mov_b64 s[12:13], 0x69a4080
	v_lshl_add_u64 v[244:245], v[66:67], 0, s[2:3]
	v_lshl_add_u64 v[244:245], v[244:245], 0, s[12:13]
	v_readfirstlane_b32 s12, v243
	s_mov_b32 m0, s12
	s_nop 0
	global_load_lds_dwordx4 v[244:245], off
	v_add_u32_e32 v243, 0xa000, v246
	s_mov_b64 s[12:13], 0x69ac080
	v_lshl_add_u64 v[244:245], v[66:67], 0, s[2:3]
	v_lshl_add_u64 v[244:245], v[244:245], 0, s[12:13]
	v_readfirstlane_b32 s12, v243
	s_mov_b32 m0, s12
	s_nop 0
	global_load_lds_dwordx4 v[244:245], off
	s_add_u32 s2, s2, 0x80
	s_addc_u32 s3, s3, 0
	s_waitcnt vmcnt(6) lgkmcnt(0)
	s_barrier
	v_mov_b32_e32 v184, v78
	v_mov_b32_e32 v154, v77
	v_add_u32_e32 v246, 0x18000, v72
	v_add_u32_e32 v181, v184, v75
	ds_read_b128 v[80:83], v181 offset:0x0
	ds_read_b128 v[88:91], v181 offset:0x1000
	ds_read_b128 v[96:99], v181 offset:0x2000
	ds_read_b128 v[100:103], v181 offset:0x3000
	v_add_u32_e32 v181, v154, v75
	ds_read_b128 v[104:107], v181 offset:0
	v_add_u32_e32 v181, v184, v74
	ds_read_b128 v[108:111], v181 offset:0x0
	ds_read_b128 v[112:115], v181 offset:0x1000
	ds_read_b128 v[116:119], v181 offset:0x2000
	ds_read_b128 v[120:123], v181 offset:0x3000
	v_add_u32_e32 v181, v154, v74
	ds_read_b128 v[124:127], v181 offset:0
	s_waitcnt lgkmcnt(5)
	v_mfma_f32_32x32x16_bf16 v[48:63], v[80:83], v[104:107], v[48:63]
	v_lshl_add_u64 v[244:245], v[64:65], 0, s[2:3]
	v_lshl_add_u64 v[244:245], v[244:245], 0, s[16:17]
	v_readfirstlane_b32 s12, v246
	s_mov_b32 m0, s12
	s_nop 0
	global_load_lds_dwordx4 v[244:245], off
	v_mfma_f32_32x32x16_bf16 v[32:47], v[88:91], v[104:107], v[32:47]
	v_mfma_f32_32x32x16_bf16 v[0:15], v[96:99], v[104:107], v[0:15]
	v_add_u32_e32 v243, 0x2000, v246
	s_mov_b64 s[12:13], 0x8080
	v_lshl_add_u64 v[244:245], v[64:65], 0, s[2:3]
	v_lshl_add_u64 v[244:245], v[244:245], 0, s[12:13]
	v_readfirstlane_b32 s12, v243
	s_mov_b32 m0, s12
	s_nop 0
	global_load_lds_dwordx4 v[244:245], off
	v_mfma_f32_32x32x16_bf16 v[16:31], v[100:103], v[104:107], v[16:31]
	v_add_u32_e32 v181, v184, v73
	ds_read_b128 v[80:83], v181 offset:0x0
	ds_read_b128 v[88:91], v181 offset:0x1000
	ds_read_b128 v[96:99], v181 offset:0x2000
	ds_read_b128 v[100:103], v181 offset:0x3000
	v_add_u32_e32 v181, v154, v73
	ds_read_b128 v[104:107], v181 offset:0
	s_waitcnt lgkmcnt(5)
	v_mfma_f32_32x32x16_bf16 v[48:63], v[108:111], v[124:127], v[48:63]
	v_add_u32_e32 v243, 0x4000, v246
	s_mov_b64 s[12:13], 0x6994080
	v_lshl_add_u64 v[244:245], v[66:67], 0, s[2:3]
	v_lshl_add_u64 v[244:245], v[244:245], 0, s[12:13]
	v_readfirstlane_b32 s12, v243
	s_mov_b32 m0, s12
	s_nop 0
	global_load_lds_dwordx4 v[244:245], off
	v_mfma_f32_32x32x16_bf16 v[32:47], v[112:115], v[124:127], v[32:47]
	v_mfma_f32_32x32x16_bf16 v[0:15], v[116:119], v[124:127], v[0:15]
	v_add_u32_e32 v243, 0x6000, v246
	s_mov_b64 s[12:13], 0x699c080
	v_lshl_add_u64 v[244:245], v[66:67], 0, s[2:3]
	v_lshl_add_u64 v[244:245], v[244:245], 0, s[12:13]
	v_readfirstlane_b32 s12, v243
	s_mov_b32 m0, s12
	s_nop 0
	global_load_lds_dwordx4 v[244:245], off
	v_mfma_f32_32x32x16_bf16 v[16:31], v[120:123], v[124:127], v[16:31]
	v_add_u32_e32 v181, v184, v71
	ds_read_b128 v[108:111], v181 offset:0x0
	ds_read_b128 v[112:115], v181 offset:0x1000
	ds_read_b128 v[116:119], v181 offset:0x2000
	ds_read_b128 v[120:123], v181 offset:0x3000
	v_add_u32_e32 v181, v154, v71
	ds_read_b128 v[124:127], v181 offset:0
	s_waitcnt lgkmcnt(5)
	v_mfma_f32_32x32x16_bf16 v[48:63], v[80:83], v[104:107], v[48:63]
	v_add_u32_e32 v243, 0x8000, v246
	s_mov_b64 s[12:13], 0x69a4080
	v_lshl_add_u64 v[244:245], v[66:67], 0, s[2:3]
	v_lshl_add_u64 v[244:245], v[244:245], 0, s[12:13]
	v_readfirstlane_b32 s12, v243
	s_mov_b32 m0, s12
	s_nop 0
	global_load_lds_dwordx4 v[244:245], off
	v_mfma_f32_32x32x16_bf16 v[32:47], v[88:91], v[104:107], v[32:47]
	v_mfma_f32_32x32x16_bf16 v[0:15], v[96:99], v[104:107], v[0:15]
	v_add_u32_e32 v243, 0xa000, v246
	s_mov_b64 s[12:13], 0x69ac080
	v_lshl_add_u64 v[244:245], v[66:67], 0, s[2:3]
	v_lshl_add_u64 v[244:245], v[244:245], 0, s[12:13]
	v_readfirstlane_b32 s12, v243
	s_mov_b32 m0, s12
	s_nop 0
	global_load_lds_dwordx4 v[244:245], off
	v_mfma_f32_32x32x16_bf16 v[16:31], v[100:103], v[104:107], v[16:31]
	s_waitcnt lgkmcnt(0)
	v_mfma_f32_32x32x16_bf16 v[48:63], v[108:111], v[124:127], v[48:63]
	v_mfma_f32_32x32x16_bf16 v[32:47], v[112:115], v[124:127], v[32:47]
	v_mfma_f32_32x32x16_bf16 v[0:15], v[116:119], v[124:127], v[0:15]
	v_mfma_f32_32x32x16_bf16 v[16:31], v[120:123], v[124:127], v[16:31]
	s_add_u32 s2, s2, 0x80
	s_addc_u32 s3, s3, 0
	s_waitcnt vmcnt(6) lgkmcnt(0)
	s_barrier
	v_add_u32_e32 v184, 0xc000, v78
	v_add_u32_e32 v154, 0xc000, v77
	v_mov_b32_e32 v246, v72
	v_add_u32_e32 v181, v184, v75
	ds_read_b128 v[80:83], v181 offset:0x0
	ds_read_b128 v[88:91], v181 offset:0x1000
	ds_read_b128 v[96:99], v181 offset:0x2000
	ds_read_b128 v[100:103], v181 offset:0x3000
	v_add_u32_e32 v181, v154, v75
	ds_read_b128 v[104:107], v181 offset:0
	v_add_u32_e32 v181, v184, v74
	ds_read_b128 v[108:111], v181 offset:0x0
	ds_read_b128 v[112:115], v181 offset:0x1000
	ds_read_b128 v[116:119], v181 offset:0x2000
	ds_read_b128 v[120:123], v181 offset:0x3000
	v_add_u32_e32 v181, v154, v74
	ds_read_b128 v[124:127], v181 offset:0
	s_waitcnt lgkmcnt(5)
	v_mfma_f32_32x32x16_bf16 v[48:63], v[80:83], v[104:107], v[48:63]
	v_lshl_add_u64 v[244:245], v[64:65], 0, s[2:3]
	v_lshl_add_u64 v[244:245], v[244:245], 0, s[16:17]
	v_readfirstlane_b32 s12, v246
	s_mov_b32 m0, s12
	s_nop 0
	global_load_lds_dwordx4 v[244:245], off
	v_mfma_f32_32x32x16_bf16 v[32:47], v[88:91], v[104:107], v[32:47]
	v_mfma_f32_32x32x16_bf16 v[0:15], v[96:99], v[104:107], v[0:15]
	v_add_u32_e32 v243, 0x2000, v246
	s_mov_b64 s[12:13], 0x8080
	v_lshl_add_u64 v[244:245], v[64:65], 0, s[2:3]
	v_lshl_add_u64 v[244:245], v[244:245], 0, s[12:13]
	v_readfirstlane_b32 s12, v243
	s_mov_b32 m0, s12
	s_nop 0
	global_load_lds_dwordx4 v[244:245], off
	v_mfma_f32_32x32x16_bf16 v[16:31], v[100:103], v[104:107], v[16:31]
	v_add_u32_e32 v181, v184, v73
	ds_read_b128 v[80:83], v181 offset:0x0
	ds_read_b128 v[88:91], v181 offset:0x1000
	ds_read_b128 v[96:99], v181 offset:0x2000
	ds_read_b128 v[100:103], v181 offset:0x3000
	v_add_u32_e32 v181, v154, v73
	ds_read_b128 v[104:107], v181 offset:0
	s_waitcnt lgkmcnt(5)
	v_mfma_f32_32x32x16_bf16 v[48:63], v[108:111], v[124:127], v[48:63]
	v_add_u32_e32 v243, 0x4000, v246
	s_mov_b64 s[12:13], 0x6994080
	v_lshl_add_u64 v[244:245], v[66:67], 0, s[2:3]
	v_lshl_add_u64 v[244:245], v[244:245], 0, s[12:13]
	v_readfirstlane_b32 s12, v243
	s_mov_b32 m0, s12
	s_nop 0
	global_load_lds_dwordx4 v[244:245], off
	v_mfma_f32_32x32x16_bf16 v[32:47], v[112:115], v[124:127], v[32:47]
	v_mfma_f32_32x32x16_bf16 v[0:15], v[116:119], v[124:127], v[0:15]
	v_add_u32_e32 v243, 0x6000, v246
	s_mov_b64 s[12:13], 0x699c080
	v_lshl_add_u64 v[244:245], v[66:67], 0, s[2:3]
	v_lshl_add_u64 v[244:245], v[244:245], 0, s[12:13]
	v_readfirstlane_b32 s12, v243
	s_mov_b32 m0, s12
	s_nop 0
	global_load_lds_dwordx4 v[244:245], off
	v_mfma_f32_32x32x16_bf16 v[16:31], v[120:123], v[124:127], v[16:31]
	v_add_u32_e32 v181, v184, v71
	ds_read_b128 v[108:111], v181 offset:0x0
	ds_read_b128 v[112:115], v181 offset:0x1000
	ds_read_b128 v[116:119], v181 offset:0x2000
	ds_read_b128 v[120:123], v181 offset:0x3000
	v_add_u32_e32 v181, v154, v71
	ds_read_b128 v[124:127], v181 offset:0
	s_waitcnt lgkmcnt(5)
	v_mfma_f32_32x32x16_bf16 v[48:63], v[80:83], v[104:107], v[48:63]
	v_add_u32_e32 v243, 0x8000, v246
	s_mov_b64 s[12:13], 0x69a4080
	v_lshl_add_u64 v[244:245], v[66:67], 0, s[2:3]
	v_lshl_add_u64 v[244:245], v[244:245], 0, s[12:13]
	v_readfirstlane_b32 s12, v243
	s_mov_b32 m0, s12
	s_nop 0
	global_load_lds_dwordx4 v[244:245], off
	v_mfma_f32_32x32x16_bf16 v[32:47], v[88:91], v[104:107], v[32:47]
	v_mfma_f32_32x32x16_bf16 v[0:15], v[96:99], v[104:107], v[0:15]
	v_add_u32_e32 v243, 0xa000, v246
	s_mov_b64 s[12:13], 0x69ac080
	v_lshl_add_u64 v[244:245], v[66:67], 0, s[2:3]
	v_lshl_add_u64 v[244:245], v[244:245], 0, s[12:13]
	v_readfirstlane_b32 s12, v243
	s_mov_b32 m0, s12
	s_nop 0
	global_load_lds_dwordx4 v[244:245], off
	v_mfma_f32_32x32x16_bf16 v[16:31], v[100:103], v[104:107], v[16:31]
	s_waitcnt lgkmcnt(0)
	v_mfma_f32_32x32x16_bf16 v[48:63], v[108:111], v[124:127], v[48:63]
	v_mfma_f32_32x32x16_bf16 v[32:47], v[112:115], v[124:127], v[32:47]
	v_mfma_f32_32x32x16_bf16 v[0:15], v[116:119], v[124:127], v[0:15]
	v_mfma_f32_32x32x16_bf16 v[16:31], v[120:123], v[124:127], v[16:31]
	s_add_u32 s2, s2, 0x80
	s_addc_u32 s3, s3, 0
	s_waitcnt vmcnt(6) lgkmcnt(0)
	s_barrier
	v_add_u32_e32 v184, 0x18000, v78
	v_add_u32_e32 v154, 0x18000, v77
	v_add_u32_e32 v181, v184, v75
	ds_read_b128 v[80:83], v181 offset:0x0
	ds_read_b128 v[88:91], v181 offset:0x1000
	ds_read_b128 v[96:99], v181 offset:0x2000
	ds_read_b128 v[100:103], v181 offset:0x3000
	v_add_u32_e32 v181, v154, v75
	ds_read_b128 v[104:107], v181 offset:0
	v_add_u32_e32 v181, v184, v74
	ds_read_b128 v[108:111], v181 offset:0x0
	ds_read_b128 v[112:115], v181 offset:0x1000
	ds_read_b128 v[116:119], v181 offset:0x2000
	ds_read_b128 v[120:123], v181 offset:0x3000
	v_add_u32_e32 v181, v154, v74
	ds_read_b128 v[124:127], v181 offset:0
	s_waitcnt lgkmcnt(5)
	v_mfma_f32_32x32x16_bf16 v[48:63], v[80:83], v[104:107], v[48:63]
	v_mfma_f32_32x32x16_bf16 v[32:47], v[88:91], v[104:107], v[32:47]
	v_mfma_f32_32x32x16_bf16 v[0:15], v[96:99], v[104:107], v[0:15]
	v_mfma_f32_32x32x16_bf16 v[16:31], v[100:103], v[104:107], v[16:31]
	v_add_u32_e32 v181, v184, v73
	ds_read_b128 v[80:83], v181 offset:0x0
	ds_read_b128 v[88:91], v181 offset:0x1000
	ds_read_b128 v[96:99], v181 offset:0x2000
	ds_read_b128 v[100:103], v181 offset:0x3000
	v_add_u32_e32 v181, v154, v73
	ds_read_b128 v[104:107], v181 offset:0
	s_waitcnt lgkmcnt(5)
	v_mfma_f32_32x32x16_bf16 v[48:63], v[108:111], v[124:127], v[48:63]
	v_mfma_f32_32x32x16_bf16 v[32:47], v[112:115], v[124:127], v[32:47]
	v_mfma_f32_32x32x16_bf16 v[0:15], v[116:119], v[124:127], v[0:15]
	v_mfma_f32_32x32x16_bf16 v[16:31], v[120:123], v[124:127], v[16:31]
	v_add_u32_e32 v181, v184, v71
	ds_read_b128 v[108:111], v181 offset:0x0
	ds_read_b128 v[112:115], v181 offset:0x1000
	ds_read_b128 v[116:119], v181 offset:0x2000
	ds_read_b128 v[120:123], v181 offset:0x3000
	v_add_u32_e32 v181, v154, v71
	ds_read_b128 v[124:127], v181 offset:0
	s_waitcnt lgkmcnt(5)
	v_mfma_f32_32x32x16_bf16 v[48:63], v[80:83], v[104:107], v[48:63]
	v_mfma_f32_32x32x16_bf16 v[32:47], v[88:91], v[104:107], v[32:47]
	v_mfma_f32_32x32x16_bf16 v[0:15], v[96:99], v[104:107], v[0:15]
	v_mfma_f32_32x32x16_bf16 v[16:31], v[100:103], v[104:107], v[16:31]
	s_waitcnt lgkmcnt(0)
	v_mfma_f32_32x32x16_bf16 v[48:63], v[108:111], v[124:127], v[48:63]
	v_mfma_f32_32x32x16_bf16 v[32:47], v[112:115], v[124:127], v[32:47]
	v_mfma_f32_32x32x16_bf16 v[0:15], v[116:119], v[124:127], v[0:15]
	v_mfma_f32_32x32x16_bf16 v[16:31], v[120:123], v[124:127], v[16:31]
	s_waitcnt vmcnt(0) lgkmcnt(0)
	s_barrier
	v_mov_b32_e32 v184, v78
	v_mov_b32_e32 v154, v77
	v_add_u32_e32 v181, v184, v75
	ds_read_b128 v[80:83], v181 offset:0x0
	ds_read_b128 v[88:91], v181 offset:0x1000
	ds_read_b128 v[96:99], v181 offset:0x2000
	ds_read_b128 v[100:103], v181 offset:0x3000
	v_add_u32_e32 v181, v154, v75
	ds_read_b128 v[104:107], v181 offset:0
	v_add_u32_e32 v181, v184, v74
	ds_read_b128 v[108:111], v181 offset:0x0
	ds_read_b128 v[112:115], v181 offset:0x1000
	ds_read_b128 v[116:119], v181 offset:0x2000
	ds_read_b128 v[120:123], v181 offset:0x3000
	v_add_u32_e32 v181, v154, v74
	ds_read_b128 v[124:127], v181 offset:0
	s_waitcnt lgkmcnt(5)
	v_mfma_f32_32x32x16_bf16 v[48:63], v[80:83], v[104:107], v[48:63]
	v_mfma_f32_32x32x16_bf16 v[32:47], v[88:91], v[104:107], v[32:47]
	v_mfma_f32_32x32x16_bf16 v[0:15], v[96:99], v[104:107], v[0:15]
	v_mfma_f32_32x32x16_bf16 v[16:31], v[100:103], v[104:107], v[16:31]
	v_add_u32_e32 v181, v184, v73
	ds_read_b128 v[80:83], v181 offset:0x0
	ds_read_b128 v[88:91], v181 offset:0x1000
	ds_read_b128 v[96:99], v181 offset:0x2000
	ds_read_b128 v[100:103], v181 offset:0x3000
	v_add_u32_e32 v181, v154, v73
	ds_read_b128 v[104:107], v181 offset:0
	s_waitcnt lgkmcnt(5)
	v_mfma_f32_32x32x16_bf16 v[48:63], v[108:111], v[124:127], v[48:63]
	v_mfma_f32_32x32x16_bf16 v[32:47], v[112:115], v[124:127], v[32:47]
	v_mfma_f32_32x32x16_bf16 v[0:15], v[116:119], v[124:127], v[0:15]
	v_mfma_f32_32x32x16_bf16 v[16:31], v[120:123], v[124:127], v[16:31]
	v_add_u32_e32 v181, v184, v71
	ds_read_b128 v[108:111], v181 offset:0x0
	ds_read_b128 v[112:115], v181 offset:0x1000
	ds_read_b128 v[116:119], v181 offset:0x2000
	ds_read_b128 v[120:123], v181 offset:0x3000
	v_add_u32_e32 v181, v154, v71
	ds_read_b128 v[124:127], v181 offset:0
	s_waitcnt lgkmcnt(5)
	v_mfma_f32_32x32x16_bf16 v[48:63], v[80:83], v[104:107], v[48:63]
	v_mfma_f32_32x32x16_bf16 v[32:47], v[88:91], v[104:107], v[32:47]
	v_mfma_f32_32x32x16_bf16 v[0:15], v[96:99], v[104:107], v[0:15]
	v_mfma_f32_32x32x16_bf16 v[16:31], v[100:103], v[104:107], v[16:31]
	s_waitcnt lgkmcnt(0)
	v_mfma_f32_32x32x16_bf16 v[48:63], v[108:111], v[124:127], v[48:63]
	v_mfma_f32_32x32x16_bf16 v[32:47], v[112:115], v[124:127], v[32:47]
	v_mfma_f32_32x32x16_bf16 v[0:15], v[116:119], v[124:127], v[0:15]
	v_mfma_f32_32x32x16_bf16 v[16:31], v[120:123], v[124:127], v[16:31]
	v_add_u32_e32 v64, s10, v69
	v_ashrrev_i32_e32 v69, 7, v64
	v_or_b32_e32 v64, s9, v68
	v_add_u32_e32 v64, v70, v64
	s_barrier
	s_andn2_b64 vcc, exec, s[0:1]
	s_mov_b64 s[0:1], -1
	s_cbranch_vccnz .LBB0_498
	v_ashrrev_i32_e32 v65, 8, v64
	v_lshl_add_u32 v68, v65, 3, v69
	s_movk_i32 s0, 0x500
	v_lshl_add_u32 v65, v65, 9, s72
	v_mad_i64_i32 v[70:71], s[0:1], v68, s0, 0
	v_or_b32_sdwa v66, v65, v64 dst_sel:DWORD dst_unused:UNUSED_PAD src0_sel:DWORD src1_sel:BYTE_0
	v_ashrrev_i32_e32 v67, 31, v66
	v_readlane_b32 s0, v242, 58
	v_or_b32_sdwa v70, v70, v64 dst_sel:DWORD dst_unused:UNUSED_PAD src0_sel:DWORD src1_sel:BYTE_0
	v_lshlrev_b64 v[66:67], 7, v[66:67]
	v_readlane_b32 s1, v242, 59
	v_mov_b64_e32 v[72:73], s[58:59]
	s_movk_i32 s2, 0xc0
	v_lshl_add_u64 v[66:67], s[0:1], 0, v[66:67]
	v_mad_u64_u32 v[84:85], s[0:1], v70, s2, v[72:73]
	v_mad_i32_i24 v85, v71, s2, v85
	v_mov_b64_e32 v[70:71], s[62:63]
	s_mov_b32 s0, 0x28000
	v_mad_i64_i32 v[70:71], s[0:1], v68, s0, v[70:71]
	v_lshlrev_b32_sdwa v128, v166, v64 dst_sel:DWORD dst_unused:UNUSED_PAD src0_sel:DWORD src1_sel:BYTE_0
	v_lshl_add_u64 v[80:81], v[70:71], 0, v[128:129]
	s_mov_b64 s[0:1], 0

.LBB0_975:
	s_or_b64 exec, exec, s[0:1]
	s_andn2_saveexec_b64 s[0:1], s[2:3]
	s_cbranch_execz .LBB0_829
	s_branch .LBB0_977
.Ltramp_270:
	s_branch .LBB0_270
.LBB0_976:
	s_andn2_saveexec_b64 s[0:1], s[2:3]
	s_cbranch_execz .LBB0_829
